# MoBA loops: one static s_setprio 1 for waves 4-7 before the loop, per-segment flips replaced by s_nop (section 7.4 recipe)
# speedup vs baseline: 1.0009x; 1.0009x over previous
.LBB0_262:
	s_setprio 0
	v_mov_b32_e32 v0, v212
	s_nop 1
	v_permlane32_swap_b32_e32 v212, v0
	v_add_f32_e32 v0, v212, v0
	v_div_scale_f32 v2, s[0:1], v0, v0, 1.0
	v_rcp_f32_e32 v4, v2
	v_add3_u32 v8, s61, v177, v176
	v_lshlrev_b32_e32 v9, 4, v145
	s_waitcnt vmcnt(0)
	v_fma_f32 v3, -v2, v4, 1.0
	v_fmac_f32_e32 v4, v3, v4
	v_div_scale_f32 v3, vcc, 1.0, v0, 1.0
	v_mul_f32_e32 v5, v3, v4
	v_fma_f32 v6, -v2, v5, v3
	v_fmac_f32_e32 v5, v6, v4
	v_add_u32_e32 v10, v8, v9
	v_fma_f32 v6, -v2, v5, v3
	ds_read_b64 v[2:3], v10
	v_div_fmas_f32 v4, v6, v4, v5
	v_div_fixup_f32 v0, v4, v0, 1.0
	v_pk_mul_f32 v[4:5], v[64:65], v[0:1] op_sel_hi:[1,0]
	s_mulk_i32 s90, 0x1400
	s_waitcnt lgkmcnt(0)
	v_lshlrev_b32_e32 v6, 16, v2
	v_and_b32_e32 v7, 0xffff0000, v2
	v_pk_mul_f32 v[4:5], v[4:5], v[6:7]
	v_lshlrev_b32_e32 v6, 16, v3
	v_cvt_pk_bf16_f32 v2, v4, v5
	v_pk_mul_f32 v[4:5], v[66:67], v[0:1] op_sel_hi:[1,0]
	v_and_b32_e32 v7, 0xffff0000, v3
	v_pk_mul_f32 v[4:5], v[4:5], v[6:7]
	s_mul_hi_u32 s0, s89, 0x1400
	v_cvt_pk_bf16_f32 v3, v4, v5
	ds_write_b64 v10, v[2:3]
	v_xad_u32 v10, v9, 16, v8
	ds_read_b64 v[2:3], v10
	v_pk_mul_f32 v[4:5], v[68:69], v[0:1] op_sel_hi:[1,0]
	s_add_i32 s0, s0, s90
	s_mulk_i32 s89, 0x1400
	s_add_u32 s1, s30, s89
	s_waitcnt lgkmcnt(0)
	v_lshlrev_b32_e32 v6, 16, v2
	v_and_b32_e32 v7, 0xffff0000, v2
	v_pk_mul_f32 v[4:5], v[4:5], v[6:7]
	v_lshlrev_b32_e32 v6, 16, v3
	v_cvt_pk_bf16_f32 v2, v4, v5
	v_pk_mul_f32 v[4:5], v[70:71], v[0:1] op_sel_hi:[1,0]
	v_and_b32_e32 v7, 0xffff0000, v3
	v_pk_mul_f32 v[4:5], v[4:5], v[6:7]
	s_addc_u32 s2, s31, s0
	v_cvt_pk_bf16_f32 v3, v4, v5
	ds_write_b64 v10, v[2:3]
	v_xad_u32 v10, v9, 32, v8
	ds_read_b64 v[2:3], v10
	v_pk_mul_f32 v[4:5], v[72:73], v[0:1] op_sel_hi:[1,0]
	s_add_u32 s0, s1, s60
	s_addc_u32 s1, s2, 0
	v_mov_b32_e32 v145, v1
	s_waitcnt lgkmcnt(0)
	v_lshlrev_b32_e32 v6, 16, v2
	v_and_b32_e32 v7, 0xffff0000, v2
	v_pk_mul_f32 v[4:5], v[4:5], v[6:7]
	v_lshlrev_b32_e32 v6, 16, v3
	v_cvt_pk_bf16_f32 v2, v4, v5
	v_pk_mul_f32 v[4:5], v[74:75], v[0:1] op_sel_hi:[1,0]
	v_and_b32_e32 v7, 0xffff0000, v3
	v_pk_mul_f32 v[4:5], v[4:5], v[6:7]
	s_mov_b64 s[2:3], s[22:23]
	v_cvt_pk_bf16_f32 v3, v4, v5
	ds_write_b64 v10, v[2:3]
	v_xad_u32 v10, v9, 48, v8
	ds_read_b64 v[2:3], v10
	v_pk_mul_f32 v[4:5], v[76:77], v[0:1] op_sel_hi:[1,0]
	s_waitcnt lgkmcnt(0)
	v_lshlrev_b32_e32 v6, 16, v2
	v_and_b32_e32 v7, 0xffff0000, v2
	v_pk_mul_f32 v[4:5], v[4:5], v[6:7]
	v_lshlrev_b32_e32 v6, 16, v3
	v_cvt_pk_bf16_f32 v2, v4, v5
	v_pk_mul_f32 v[4:5], v[78:79], v[0:1] op_sel_hi:[1,0]
	v_and_b32_e32 v7, 0xffff0000, v3
	v_pk_mul_f32 v[4:5], v[4:5], v[6:7]
	s_nop 0
	v_cvt_pk_bf16_f32 v3, v4, v5
	ds_write_b64 v10, v[2:3]
	v_xad_u32 v10, v9, 64, v8
	ds_read_b64 v[2:3], v10
	v_pk_mul_f32 v[4:5], v[48:49], v[0:1] op_sel_hi:[1,0]
	s_waitcnt lgkmcnt(0)
	v_lshlrev_b32_e32 v6, 16, v2
	v_and_b32_e32 v7, 0xffff0000, v2
	v_pk_mul_f32 v[4:5], v[4:5], v[6:7]
	v_lshlrev_b32_e32 v6, 16, v3
	v_cvt_pk_bf16_f32 v2, v4, v5
	v_pk_mul_f32 v[4:5], v[50:51], v[0:1] op_sel_hi:[1,0]
	v_and_b32_e32 v7, 0xffff0000, v3
	v_pk_mul_f32 v[4:5], v[4:5], v[6:7]
	s_nop 0
	v_cvt_pk_bf16_f32 v3, v4, v5
	ds_write_b64 v10, v[2:3]
	v_xad_u32 v10, v9, s69, v8
	ds_read_b64 v[2:3], v10
	v_pk_mul_f32 v[4:5], v[52:53], v[0:1] op_sel_hi:[1,0]
	s_waitcnt lgkmcnt(0)
	v_lshlrev_b32_e32 v6, 16, v2
	v_and_b32_e32 v7, 0xffff0000, v2
	v_pk_mul_f32 v[4:5], v[4:5], v[6:7]
	v_lshlrev_b32_e32 v6, 16, v3
	v_cvt_pk_bf16_f32 v2, v4, v5
	v_pk_mul_f32 v[4:5], v[54:55], v[0:1] op_sel_hi:[1,0]
	v_and_b32_e32 v7, 0xffff0000, v3
	v_pk_mul_f32 v[4:5], v[4:5], v[6:7]
	s_nop 0
	v_cvt_pk_bf16_f32 v3, v4, v5
	ds_write_b64 v10, v[2:3]
	v_xad_u32 v10, v9, s70, v8
	ds_read_b64 v[2:3], v10
	v_pk_mul_f32 v[4:5], v[56:57], v[0:1] op_sel_hi:[1,0]
	s_waitcnt lgkmcnt(0)
	v_lshlrev_b32_e32 v6, 16, v2
	v_and_b32_e32 v7, 0xffff0000, v2
	v_pk_mul_f32 v[4:5], v[4:5], v[6:7]
	v_lshlrev_b32_e32 v6, 16, v3
	v_cvt_pk_bf16_f32 v2, v4, v5
	v_pk_mul_f32 v[4:5], v[58:59], v[0:1] op_sel_hi:[1,0]
	v_and_b32_e32 v7, 0xffff0000, v3
	v_pk_mul_f32 v[4:5], v[4:5], v[6:7]
	s_nop 0
	v_cvt_pk_bf16_f32 v3, v4, v5
	ds_write_b64 v10, v[2:3]
	v_xad_u32 v10, v9, s71, v8
	ds_read_b64 v[2:3], v10
	v_pk_mul_f32 v[4:5], v[60:61], v[0:1] op_sel_hi:[1,0]
	s_waitcnt lgkmcnt(0)
	v_lshlrev_b32_e32 v6, 16, v2
	v_and_b32_e32 v7, 0xffff0000, v2
	v_pk_mul_f32 v[4:5], v[4:5], v[6:7]
	v_lshlrev_b32_e32 v6, 16, v3
	v_cvt_pk_bf16_f32 v2, v4, v5
	v_pk_mul_f32 v[4:5], v[62:63], v[0:1] op_sel_hi:[1,0]
	v_and_b32_e32 v7, 0xffff0000, v3
	v_pk_mul_f32 v[4:5], v[4:5], v[6:7]
	s_nop 0
	v_cvt_pk_bf16_f32 v3, v4, v5
	ds_write_b64 v10, v[2:3]
	v_xad_u32 v10, v9, s72, v8
	ds_read_b64 v[2:3], v10
	v_pk_mul_f32 v[4:5], v[32:33], v[0:1] op_sel_hi:[1,0]
	s_waitcnt lgkmcnt(0)
	v_lshlrev_b32_e32 v6, 16, v2
	v_and_b32_e32 v7, 0xffff0000, v2
	v_pk_mul_f32 v[4:5], v[4:5], v[6:7]
	v_lshlrev_b32_e32 v6, 16, v3
	v_cvt_pk_bf16_f32 v2, v4, v5
	v_pk_mul_f32 v[4:5], v[34:35], v[0:1] op_sel_hi:[1,0]
	v_and_b32_e32 v7, 0xffff0000, v3
	v_pk_mul_f32 v[4:5], v[4:5], v[6:7]
	s_nop 0
	v_cvt_pk_bf16_f32 v3, v4, v5
	ds_write_b64 v10, v[2:3]
	v_xad_u32 v10, v9, s73, v8
	ds_read_b64 v[2:3], v10
	v_pk_mul_f32 v[4:5], v[36:37], v[0:1] op_sel_hi:[1,0]
	s_waitcnt lgkmcnt(0)
	v_lshlrev_b32_e32 v6, 16, v2
	v_and_b32_e32 v7, 0xffff0000, v2
	v_pk_mul_f32 v[4:5], v[4:5], v[6:7]
	v_lshlrev_b32_e32 v6, 16, v3
	v_cvt_pk_bf16_f32 v2, v4, v5
	v_pk_mul_f32 v[4:5], v[38:39], v[0:1] op_sel_hi:[1,0]
	v_and_b32_e32 v7, 0xffff0000, v3
	v_pk_mul_f32 v[4:5], v[4:5], v[6:7]
	s_nop 0
	v_cvt_pk_bf16_f32 v3, v4, v5
	ds_write_b64 v10, v[2:3]
	v_xad_u32 v10, v9, s79, v8
	ds_read_b64 v[2:3], v10
	v_pk_mul_f32 v[4:5], v[40:41], v[0:1] op_sel_hi:[1,0]
	s_waitcnt lgkmcnt(0)
	v_lshlrev_b32_e32 v6, 16, v2
	v_and_b32_e32 v7, 0xffff0000, v2
	v_pk_mul_f32 v[4:5], v[4:5], v[6:7]
	v_lshlrev_b32_e32 v6, 16, v3
	v_cvt_pk_bf16_f32 v2, v4, v5
	v_pk_mul_f32 v[4:5], v[42:43], v[0:1] op_sel_hi:[1,0]
	v_and_b32_e32 v7, 0xffff0000, v3
	v_pk_mul_f32 v[4:5], v[4:5], v[6:7]
	s_nop 0
	v_cvt_pk_bf16_f32 v3, v4, v5
	ds_write_b64 v10, v[2:3]
	v_xad_u32 v10, v9, s80, v8
	ds_read_b64 v[2:3], v10
	v_pk_mul_f32 v[4:5], v[44:45], v[0:1] op_sel_hi:[1,0]
	s_waitcnt lgkmcnt(0)
	v_lshlrev_b32_e32 v6, 16, v2
	v_and_b32_e32 v7, 0xffff0000, v2
	v_pk_mul_f32 v[4:5], v[4:5], v[6:7]
	v_lshlrev_b32_e32 v6, 16, v3
	v_cvt_pk_bf16_f32 v2, v4, v5
	v_pk_mul_f32 v[4:5], v[46:47], v[0:1] op_sel_hi:[1,0]
	v_and_b32_e32 v7, 0xffff0000, v3
	v_pk_mul_f32 v[4:5], v[4:5], v[6:7]
	s_nop 0
	v_cvt_pk_bf16_f32 v3, v4, v5
	ds_write_b64 v10, v[2:3]
	v_xad_u32 v10, v9, s81, v8
	ds_read_b64 v[2:3], v10
	v_pk_mul_f32 v[4:5], v[16:17], v[0:1] op_sel_hi:[1,0]
	s_waitcnt lgkmcnt(0)
	v_lshlrev_b32_e32 v6, 16, v2
	v_and_b32_e32 v7, 0xffff0000, v2
	v_pk_mul_f32 v[4:5], v[4:5], v[6:7]
	v_lshlrev_b32_e32 v6, 16, v3
	v_cvt_pk_bf16_f32 v2, v4, v5
	v_pk_mul_f32 v[4:5], v[18:19], v[0:1] op_sel_hi:[1,0]
	v_and_b32_e32 v7, 0xffff0000, v3
	v_pk_mul_f32 v[4:5], v[4:5], v[6:7]
	s_nop 0
	v_cvt_pk_bf16_f32 v3, v4, v5
	ds_write_b64 v10, v[2:3]
	v_xad_u32 v10, v9, s82, v8
	ds_read_b64 v[2:3], v10
	v_pk_mul_f32 v[4:5], v[20:21], v[0:1] op_sel_hi:[1,0]
	s_waitcnt lgkmcnt(0)
	v_lshlrev_b32_e32 v6, 16, v2
	v_and_b32_e32 v7, 0xffff0000, v2
	v_pk_mul_f32 v[4:5], v[4:5], v[6:7]
	v_lshlrev_b32_e32 v6, 16, v3
	v_cvt_pk_bf16_f32 v2, v4, v5
	v_pk_mul_f32 v[4:5], v[22:23], v[0:1] op_sel_hi:[1,0]
	v_and_b32_e32 v7, 0xffff0000, v3
	v_pk_mul_f32 v[4:5], v[4:5], v[6:7]
	s_nop 0
	v_cvt_pk_bf16_f32 v3, v4, v5
	ds_write_b64 v10, v[2:3]
	v_xad_u32 v10, v9, s83, v8
	ds_read_b64 v[2:3], v10
	v_pk_mul_f32 v[4:5], v[24:25], v[0:1] op_sel_hi:[1,0]
	v_xad_u32 v8, v9, s84, v8
	s_waitcnt lgkmcnt(0)
	v_lshlrev_b32_e32 v6, 16, v2
	v_and_b32_e32 v7, 0xffff0000, v2
	v_pk_mul_f32 v[4:5], v[4:5], v[6:7]
	v_lshlrev_b32_e32 v6, 16, v3
	v_cvt_pk_bf16_f32 v2, v4, v5
	v_pk_mul_f32 v[4:5], v[26:27], v[0:1] op_sel_hi:[1,0]
	v_and_b32_e32 v7, 0xffff0000, v3
	v_pk_mul_f32 v[4:5], v[4:5], v[6:7]
	s_nop 0
	v_cvt_pk_bf16_f32 v3, v4, v5
	ds_write_b64 v10, v[2:3]
	ds_read_b64 v[2:3], v8
	v_pk_mul_f32 v[4:5], v[28:29], v[0:1] op_sel_hi:[1,0]
	s_waitcnt lgkmcnt(0)
	v_lshlrev_b32_e32 v6, 16, v2
	v_and_b32_e32 v7, 0xffff0000, v2
	v_pk_mul_f32 v[4:5], v[4:5], v[6:7]
	v_lshlrev_b32_e32 v6, 16, v3
	v_cvt_pk_bf16_f32 v2, v4, v5
	v_pk_mul_f32 v[4:5], v[30:31], v[0:1] op_sel_hi:[1,0]
	v_and_b32_e32 v7, 0xffff0000, v3
	v_pk_mul_f32 v[4:5], v[4:5], v[6:7]
	v_lshlrev_b32_e32 v0, 4, v174
	v_cvt_pk_bf16_f32 v3, v4, v5
	v_and_b32_e32 v0, 0xf0, v0
	ds_write_b64 v8, v[2:3]
	v_add_u32_e32 v18, s61, v0
	s_waitcnt lgkmcnt(0)
	v_lshl_add_u32 v6, v170, 8, v18
	ds_read_b128 v[2:5], v6
	v_mul_u32_u24_e32 v0, 0x1400, v170
	v_lshl_add_u64 v[14:15], s[0:1], 0, v[0:1]
	v_lshl_add_u64 v[10:11], v[14:15], 0, v[144:145]
	v_lshl_add_u32 v0, v147, 8, v18
	v_mov_b32_e32 v147, v1
	s_waitcnt lgkmcnt(0)
	global_store_dwordx4 v[10:11], v[2:5], off
	v_lshl_add_u64 v[10:11], v[14:15], 0, v[146:147]
	ds_read_b128 v[6:9], v6 offset:4096
	ds_read_b128 v[2:5], v0
	v_add_co_u32_e32 v16, vcc, s86, v10
	v_lshl_add_u32 v0, v149, 8, v18
	s_nop 0
	v_addc_co_u32_e32 v17, vcc, 0, v11, vcc
	ds_read_b128 v[10:13], v0
	v_lshl_add_u64 v[14:15], v[14:15], 0, s[48:49]
	v_mov_b32_e32 v149, v1
	s_waitcnt lgkmcnt(0)
	global_store_dwordx4 v[16:17], v[2:5], off
	v_lshl_add_u32 v0, v153, 8, v18
	v_mov_b32_e32 v153, v1
	v_lshl_add_u64 v[2:3], v[14:15], 0, v[148:149]
	global_store_dwordx4 v[2:3], v[10:13], off
	ds_read_b128 v[2:5], v0
	v_lshl_add_u32 v0, v151, 8, v18
	v_lshl_add_u64 v[10:11], v[14:15], 0, v[152:153]
	v_add_co_u32_e32 v14, vcc, s86, v10
	v_mov_b32_e32 v151, v1
	s_nop 0
	v_addc_co_u32_e32 v15, vcc, 0, v11, vcc
	ds_read_b128 v[10:13], v0
	v_mad_u32_u24 v0, v170, s85, v196
	s_waitcnt lgkmcnt(0)
	global_store_dwordx4 v[14:15], v[2:5], off
	s_nop 1
	v_lshl_add_u64 v[2:3], s[0:1], 0, v[0:1]
	v_lshl_add_u64 v[2:3], v[2:3], 0, v[144:145]
	v_mad_u32_u24 v0, v170, s85, v197
	global_store_dwordx4 v[2:3], v[6:9], off
	v_lshl_add_u64 v[2:3], s[0:1], 0, v[0:1]
	v_lshl_add_u64 v[2:3], v[2:3], 0, v[150:151]
	v_lshl_add_u32 v0, v155, 8, v18
	global_store_dwordx4 v[2:3], v[10:13], off
	ds_read_b128 v[2:5], v0
	v_mad_u32_u24 v0, v170, s85, v198
	v_lshl_add_u64 v[6:7], s[0:1], 0, v[0:1]
	v_mov_b32_e32 v155, v1
	v_lshl_add_u32 v0, v157, 8, v18
	v_lshl_add_u64 v[10:11], v[6:7], 0, v[154:155]
	ds_read_b128 v[6:9], v0
	v_mad_u32_u24 v0, v170, s85, v199
	s_waitcnt lgkmcnt(0)
	global_store_dwordx4 v[10:11], v[2:5], off
	v_mov_b32_e32 v157, v1
	s_nop 0
	v_lshl_add_u64 v[2:3], s[0:1], 0, v[0:1]
	v_lshl_add_u64 v[2:3], v[2:3], 0, v[156:157]
	global_store_dwordx4 v[2:3], v[6:9], off
	s_waitcnt lgkmcnt(0)

.LBB0_289:
	s_or_b64 exec, exec, s[54:55]
	v_lshlrev_b32_e32 v3, 3, v13
	v_lshl_add_u64 v[162:163], s[52:53], 0, v[0:1]
	v_lshlrev_b32_e32 v0, 1, v3
	v_and_b32_e32 v174, 63, v2
	v_lshl_add_u64 v[168:169], s[2:3], 0, v[0:1]
	v_lshlrev_b32_e32 v179, 2, v10
	v_bfe_u32 v0, v2, 2, 2
	v_lshrrev_b32_e32 v3, 3, v2
	v_bfe_u32 v2, v2, 1, 1
	v_lshl_add_u64 v[166:167], s[52:53], 0, v[4:5]
	v_and_or_b32 v2, v3, 2, v2
	v_lshlrev_b32_e32 v3, 2, v0
	v_lshlrev_b32_e32 v5, 3, v174
	v_or_b32_e32 v0, v179, v0
	v_or_b32_e32 v4, v3, v10
	v_and_b32_e32 v180, 8, v5
	v_xor_b32_e32 v5, v10, v145
	v_lshlrev_b32_e32 v202, 8, v0
	v_bitop3_b32 v0, v3, v2, v10 bitop3:0x36
	v_lshlrev_b32_e32 v181, 4, v5
	v_bitop3_b32 v5, v10, v145, 2 bitop3:0x36
	v_lshlrev_b32_e32 v203, 4, v0
	v_bitop3_b32 v0, v4, v2, 2 bitop3:0x36
	v_lshlrev_b32_e32 v182, 4, v5
	v_bitop3_b32 v5, v10, v145, 4 bitop3:0x36
	v_lshlrev_b32_e32 v204, 4, v0
	v_or_b32_e32 v0, 4, v2
	v_lshlrev_b32_e32 v183, 4, v5
	v_bitop3_b32 v5, v10, v145, 6 bitop3:0x36
	v_bitop3_b32 v0, v4, v0, 2 bitop3:0x36
	v_lshlrev_b32_e32 v184, 4, v5
	v_bitop3_b32 v5, v10, v145, 8 bitop3:0x36
	v_lshlrev_b32_e32 v206, 4, v0
	v_or_b32_e32 v0, 8, v2
	v_lshlrev_b32_e32 v185, 4, v5
	v_bitop3_b32 v5, v10, v145, 10 bitop3:0x36
	v_bitop3_b32 v0, v4, v0, 2 bitop3:0x36
	v_lshlrev_b32_e32 v186, 4, v5
	v_bitop3_b32 v5, v10, v145, 12 bitop3:0x36
	v_bitop3_b32 v3, v2, v4, 4 bitop3:0x36
	v_lshlrev_b32_e32 v208, 4, v0
	v_or_b32_e32 v0, 12, v2
	v_lshlrev_b32_e32 v6, 3, v12
	v_mov_b32_e32 v7, v1
	v_lshlrev_b32_e32 v200, 4, v5
	v_bitop3_b32 v5, v10, v145, 14 bitop3:0x36
	v_lshlrev_b32_e32 v205, 4, v3
	v_bitop3_b32 v3, v2, v4, 8 bitop3:0x36
	v_bitop3_b32 v2, v2, v4, 12 bitop3:0x36
	v_bitop3_b32 v0, v4, v0, 2 bitop3:0x36
	v_mov_b32_e32 v14, v1
	v_mov_b32_e32 v15, v1
	v_lshlrev_b32_e32 v176, 3, v10
	s_lshl_b32 s56, s94, 2
	v_lshl_add_u64 v[164:165], v[6:7], 1, s[2:3]
	v_lshlrev_b32_e32 v177, 8, v11
	v_lshlrev_b32_e32 v201, 4, v5
	v_lshlrev_b32_e32 v207, 4, v3
	v_lshlrev_b32_e32 v209, 4, v2
	v_lshlrev_b32_e32 v210, 4, v0
	v_mov_b32_e32 v0, v1
	v_mov_b32_e32 v2, v1
	v_mov_b32_e32 v3, v1
	v_mov_b32_e32 v4, v1
	v_mov_b32_e32 v5, v1
	v_mov_b32_e32 v6, v1
	v_mov_b32_e32 v8, v1
	v_mov_b32_e32 v9, v1
	v_mov_b32_e32 v10, v1
	v_mov_b32_e32 v11, v1
	v_mov_b32_e32 v12, v1
	v_mov_b32_e32 v13, v1
	v_mov_b64_e32 v[30:31], v[14:15]
	v_mov_b64_e32 v[46:47], v[14:15]
	v_mov_b64_e32 v[62:63], v[14:15]
	v_mov_b64_e32 v[78:79], v[14:15]
	v_or_b32_e32 v147, 4, v170
	v_or_b32_e32 v149, 8, v170
	v_or_b32_e32 v153, 12, v170
	v_or_b32_e32 v151, 20, v170
	v_or_b32_e32 v155, 24, v170
	v_or_b32_e32 v157, 28, v170
	s_add_i32 s56, s56, 4
	s_or_b32 s57, s66, 31
	v_add_u32_e32 v178, 0, v177
	s_mov_b32 s58, 0
	v_mov_b32_e32 v211, 0
	v_mov_b32_e32 v212, 0xf149f2ca
	s_mov_b32 s59, 0
	v_mov_b64_e32 v[28:29], v[12:13]
	v_mov_b64_e32 v[26:27], v[10:11]
	v_mov_b64_e32 v[24:25], v[8:9]
	v_mov_b64_e32 v[22:23], v[6:7]
	v_mov_b64_e32 v[20:21], v[4:5]
	v_mov_b64_e32 v[18:19], v[2:3]
	v_mov_b64_e32 v[16:17], v[0:1]
	v_mov_b64_e32 v[44:45], v[12:13]
	v_mov_b64_e32 v[42:43], v[10:11]
	v_mov_b64_e32 v[40:41], v[8:9]
	v_mov_b64_e32 v[38:39], v[6:7]
	v_mov_b64_e32 v[36:37], v[4:5]
	v_mov_b64_e32 v[34:35], v[2:3]
	v_mov_b64_e32 v[32:33], v[0:1]
	v_mov_b64_e32 v[60:61], v[12:13]
	v_mov_b64_e32 v[58:59], v[10:11]
	v_mov_b64_e32 v[56:57], v[8:9]
	v_mov_b64_e32 v[54:55], v[6:7]
	v_mov_b64_e32 v[52:53], v[4:5]
	v_mov_b64_e32 v[50:51], v[2:3]
	v_mov_b64_e32 v[48:49], v[0:1]
	v_mov_b64_e32 v[76:77], v[12:13]
	v_mov_b64_e32 v[74:75], v[10:11]
	v_mov_b64_e32 v[72:73], v[8:9]
	v_mov_b64_e32 v[70:71], v[6:7]
	v_mov_b64_e32 v[68:69], v[4:5]
	v_mov_b64_e32 v[66:67], v[2:3]
	v_mov_b64_e32 v[64:65], v[0:1]
	s_mov_b32 s52, 0
	s_waitcnt vmcnt(0) lgkmcnt(0)
	s_barrier
	s_cmp_lt_u32 s95, 0x2000
	s_cbranch_scc1 .Lsprio1
	s_setprio 1
.Lsprio1:
	s_branch .LBB0_292

.LBB0_301:
	s_nop 0
	s_nop 8
	v_max_f32_e32 v0, v97, v97
	v_max_f32_e32 v2, v96, v96
	v_max_f32_e32 v0, v2, v0
	v_max3_f32 v0, v0, v98, v99
	v_max3_f32 v0, v0, v100, v101
	v_max3_f32 v0, v0, v102, v103
	v_max3_f32 v0, v0, v104, v105
	v_max3_f32 v0, v0, v106, v107
	v_max3_f32 v0, v0, v108, v109
	v_max3_f32 v0, v0, v110, v111
	v_max3_f32 v0, v0, v80, v81
	v_max3_f32 v0, v0, v82, v83
	v_max3_f32 v0, v0, v84, v85
	v_max3_f32 v0, v0, v86, v87
	v_max3_f32 v0, v0, v88, v89
	v_max3_f32 v0, v0, v90, v91
	v_max3_f32 v0, v0, v92, v93
	v_max3_f32 v0, v0, v94, v95
	v_mov_b32_e32 v2, v0
	s_nop 1
	v_permlane32_swap_b32_e32 v0, v2
	v_max3_f32 v2, v212, v0, v2
	v_sub_f32_e32 v0, v212, v2
	v_exp_f32_e32 v0, v0
	s_nop 0
	v_cmp_neq_f32_e32 vcc, 1.0, v0
	s_cbranch_vccz .LBB0_303
	v_pk_mul_f32 v[78:79], v[78:79], v[0:1] op_sel_hi:[1,0]
	v_pk_mul_f32 v[76:77], v[76:77], v[0:1] op_sel_hi:[1,0]
	v_pk_mul_f32 v[74:75], v[74:75], v[0:1] op_sel_hi:[1,0]
	v_pk_mul_f32 v[72:73], v[72:73], v[0:1] op_sel_hi:[1,0]
	v_pk_mul_f32 v[70:71], v[70:71], v[0:1] op_sel_hi:[1,0]
	v_pk_mul_f32 v[68:69], v[68:69], v[0:1] op_sel_hi:[1,0]
	v_pk_mul_f32 v[66:67], v[66:67], v[0:1] op_sel_hi:[1,0]
	v_pk_mul_f32 v[64:65], v[64:65], v[0:1] op_sel_hi:[1,0]
	v_pk_mul_f32 v[62:63], v[62:63], v[0:1] op_sel_hi:[1,0]
	v_pk_mul_f32 v[60:61], v[60:61], v[0:1] op_sel_hi:[1,0]
	v_pk_mul_f32 v[58:59], v[58:59], v[0:1] op_sel_hi:[1,0]
	v_pk_mul_f32 v[56:57], v[56:57], v[0:1] op_sel_hi:[1,0]
	v_pk_mul_f32 v[54:55], v[54:55], v[0:1] op_sel_hi:[1,0]
	v_pk_mul_f32 v[52:53], v[52:53], v[0:1] op_sel_hi:[1,0]
	v_pk_mul_f32 v[50:51], v[50:51], v[0:1] op_sel_hi:[1,0]
	v_pk_mul_f32 v[48:49], v[48:49], v[0:1] op_sel_hi:[1,0]
	v_pk_mul_f32 v[46:47], v[46:47], v[0:1] op_sel_hi:[1,0]
	v_pk_mul_f32 v[44:45], v[44:45], v[0:1] op_sel_hi:[1,0]
	v_pk_mul_f32 v[42:43], v[42:43], v[0:1] op_sel_hi:[1,0]
	v_pk_mul_f32 v[40:41], v[40:41], v[0:1] op_sel_hi:[1,0]
	v_pk_mul_f32 v[38:39], v[38:39], v[0:1] op_sel_hi:[1,0]
	v_pk_mul_f32 v[36:37], v[36:37], v[0:1] op_sel_hi:[1,0]
	v_pk_mul_f32 v[34:35], v[34:35], v[0:1] op_sel_hi:[1,0]
	v_pk_mul_f32 v[32:33], v[32:33], v[0:1] op_sel_hi:[1,0]
	v_pk_mul_f32 v[30:31], v[30:31], v[0:1] op_sel_hi:[1,0]
	v_pk_mul_f32 v[28:29], v[28:29], v[0:1] op_sel_hi:[1,0]
	v_pk_mul_f32 v[26:27], v[26:27], v[0:1] op_sel_hi:[1,0]
	v_pk_mul_f32 v[24:25], v[24:25], v[0:1] op_sel_hi:[1,0]
	v_pk_mul_f32 v[22:23], v[22:23], v[0:1] op_sel_hi:[1,0]
	v_pk_mul_f32 v[20:21], v[20:21], v[0:1] op_sel_hi:[1,0]
	v_pk_mul_f32 v[18:19], v[18:19], v[0:1] op_sel_hi:[1,0]
	v_pk_mul_f32 v[16:17], v[16:17], v[0:1] op_sel_hi:[1,0]
.LBB0_303:
	v_sub_f32_e32 v8, v82, v2
	v_sub_f32_e32 v9, v83, v2
	v_sub_f32_e32 v7, v98, v2
	v_exp_f32_e32 v98, v8
	v_sub_f32_e32 v8, v99, v2
	v_exp_f32_e32 v99, v9
	v_sub_f32_e32 v9, v100, v2
	v_exp_f32_e32 v12, v9
	v_sub_f32_e32 v9, v84, v2
	v_exp_f32_e32 v100, v9
	v_sub_f32_e32 v9, v101, v2
	v_exp_f32_e32 v13, v9
	v_sub_f32_e32 v9, v85, v2
	v_exp_f32_e32 v101, v9
	v_sub_f32_e32 v9, v102, v2
	v_exp_f32_e32 v14, v9
	v_sub_f32_e32 v9, v86, v2
	v_exp_f32_e32 v102, v9
	v_sub_f32_e32 v9, v103, v2
	v_exp_f32_e32 v15, v9
	v_sub_f32_e32 v9, v87, v2
	v_sub_f32_e32 v3, v96, v2
	v_sub_f32_e32 v4, v80, v2
	v_exp_f32_e32 v103, v9
	v_sub_f32_e32 v9, v104, v2
	v_exp_f32_e32 v3, v3
	v_exp_f32_e32 v96, v4
	v_sub_f32_e32 v4, v97, v2
	v_sub_f32_e32 v5, v81, v2
	v_exp_f32_e32 v104, v9
	v_sub_f32_e32 v9, v88, v2
	v_exp_f32_e32 v4, v4
	v_exp_f32_e32 v97, v5
	v_exp_f32_e32 v88, v9
	v_sub_f32_e32 v9, v105, v2
	v_exp_f32_e32 v7, v7
	v_exp_f32_e32 v105, v9
	v_sub_f32_e32 v9, v89, v2
	v_exp_f32_e32 v8, v8
	v_exp_f32_e32 v89, v9
	v_sub_f32_e32 v9, v106, v2
	v_add_f32_e32 v5, v3, v96
	v_exp_f32_e32 v106, v9
	v_sub_f32_e32 v9, v90, v2
	v_add_f32_e32 v5, 0, v5
	v_add_f32_e32 v6, v4, v97
	v_exp_f32_e32 v90, v9
	v_sub_f32_e32 v9, v107, v2
	v_add_f32_e32 v5, v6, v5
	v_add_f32_e32 v6, v7, v98
	v_exp_f32_e32 v107, v9
	v_sub_f32_e32 v9, v91, v2
	v_add_f32_e32 v5, v6, v5
	v_add_f32_e32 v6, v8, v99
	v_exp_f32_e32 v91, v9
	v_sub_f32_e32 v9, v108, v2
	v_add_f32_e32 v5, v6, v5
	v_add_f32_e32 v6, v12, v100
	v_exp_f32_e32 v108, v9
	v_sub_f32_e32 v9, v92, v2
	v_add_f32_e32 v5, v6, v5
	v_add_f32_e32 v6, v13, v101
	v_exp_f32_e32 v92, v9
	v_sub_f32_e32 v9, v109, v2
	v_add_f32_e32 v5, v6, v5
	v_add_f32_e32 v6, v14, v102
	v_exp_f32_e32 v109, v9
	v_sub_f32_e32 v9, v93, v2
	v_add_f32_e32 v5, v6, v5
	v_add_f32_e32 v6, v15, v103
	v_exp_f32_e32 v93, v9
	v_sub_f32_e32 v9, v110, v2
	v_add_f32_e32 v5, v6, v5
	v_add_f32_e32 v6, v104, v88
	v_exp_f32_e32 v110, v9
	v_sub_f32_e32 v9, v94, v2
	v_add_f32_e32 v5, v6, v5
	v_add_f32_e32 v6, v105, v89
	v_exp_f32_e32 v94, v9
	v_sub_f32_e32 v9, v111, v2
	v_add_f32_e32 v5, v6, v5
	v_add_f32_e32 v6, v106, v90
	v_exp_f32_e32 v111, v9
	v_sub_f32_e32 v9, v95, v2
	v_add_f32_e32 v5, v6, v5
	v_add_f32_e32 v6, v107, v91
	v_exp_f32_e32 v95, v9
	v_add_f32_e32 v5, v6, v5
	v_add_f32_e32 v6, v108, v92
	v_add_f32_e32 v5, v6, v5
	v_add_f32_e32 v6, v109, v93
	v_add_f32_e32 v5, v6, v5
	v_add_f32_e32 v6, v110, v94
	v_add_f32_e32 v5, v6, v5
	v_add_f32_e32 v6, v111, v95
	v_add_f32_e32 v212, v6, v5
	v_fmac_f32_e32 v212, v211, v0
	s_add_i32 s2, s52, 0
	s_nop 0
	v_add_u32_e32 v0, s2, v180
	v_add_u32_e32 v211, s2, v202
	v_cvt_pk_bf16_f32 v4, v3, v4
	v_add3_u32 v3, v0, v203, v202
	v_add3_u32 v86, v211, v204, v180
	v_cvt_pk_bf16_f32 v5, v7, v8
	s_nop 0
	ds_read_b64_tr_b16 v[8:9], v3 offset:32768
	ds_read_b64_tr_b16 v[10:11], v86 offset:34816
	v_cvt_pk_bf16_f32 v6, v12, v13
	v_cvt_pk_bf16_f32 v7, v14, v15
	ds_read_b64_tr_b16 v[12:13], v3 offset:36864
	ds_read_b64_tr_b16 v[80:81], v3 offset:40960
	ds_read_b64_tr_b16 v[84:85], v3 offset:45056
	ds_read_b64_tr_b16 v[14:15], v86 offset:38912
	ds_read_b64_tr_b16 v[82:83], v86 offset:43008
	ds_read_b64_tr_b16 v[86:87], v86 offset:47104
	s_waitcnt lgkmcnt(6)
	v_mfma_f32_32x32x16_bf16 v[64:79], v[8:11], v[4:7], v[64:79]
	v_cvt_pk_bf16_f32 v8, v104, v105
	v_cvt_pk_bf16_f32 v9, v106, v107
	v_cvt_pk_bf16_f32 v10, v108, v109
	v_cvt_pk_bf16_f32 v11, v110, v111
	v_add3_u32 v3, v0, v205, v202
	s_waitcnt lgkmcnt(2)
	v_mfma_f32_32x32x16_bf16 v[64:79], v[12:15], v[8:11], v[64:79]
	v_cvt_pk_bf16_f32 v12, v96, v97
	v_cvt_pk_bf16_f32 v13, v98, v99
	v_cvt_pk_bf16_f32 v14, v100, v101
	v_cvt_pk_bf16_f32 v15, v102, v103
	v_add3_u32 v100, v211, v206, v180
	s_waitcnt lgkmcnt(1)
	v_mfma_f32_32x32x16_bf16 v[64:79], v[80:83], v[12:15], v[64:79]
	v_cvt_pk_bf16_f32 v80, v88, v89
	ds_read_b64_tr_b16 v[88:89], v100 offset:34816
	v_cvt_pk_bf16_f32 v81, v90, v91
	v_cvt_pk_bf16_f32 v82, v92, v93
	v_cvt_pk_bf16_f32 v83, v94, v95
	s_waitcnt lgkmcnt(1)
	s_nop 0
	v_mfma_f32_32x32x16_bf16 v[64:79], v[84:87], v[80:83], v[64:79]
	ds_read_b64_tr_b16 v[86:87], v3 offset:32768
	ds_read_b64_tr_b16 v[90:91], v3 offset:36864
	ds_read_b64_tr_b16 v[94:95], v3 offset:40960
	ds_read_b64_tr_b16 v[98:99], v3 offset:45056
	ds_read_b64_tr_b16 v[92:93], v100 offset:38912
	ds_read_b64_tr_b16 v[96:97], v100 offset:43008
	ds_read_b64_tr_b16 v[100:101], v100 offset:47104
	v_add3_u32 v3, v0, v207, v202
	v_add3_u32 v0, v0, v209, v202
	s_waitcnt lgkmcnt(6)
	v_mfma_f32_32x32x16_bf16 v[48:63], v[86:89], v[4:7], v[48:63]
	s_waitcnt lgkmcnt(2)
	v_mfma_f32_32x32x16_bf16 v[48:63], v[90:93], v[8:11], v[48:63]
	s_waitcnt lgkmcnt(1)
	v_mfma_f32_32x32x16_bf16 v[48:63], v[94:97], v[12:15], v[48:63]
	s_waitcnt lgkmcnt(0)
	v_mfma_f32_32x32x16_bf16 v[48:63], v[98:101], v[80:83], v[48:63]
	v_add3_u32 v98, v211, v208, v180
	ds_read_b64_tr_b16 v[86:87], v98 offset:34816
	ds_read_b64_tr_b16 v[84:85], v3 offset:32768
	ds_read_b64_tr_b16 v[88:89], v3 offset:36864
	ds_read_b64_tr_b16 v[92:93], v3 offset:40960
	ds_read_b64_tr_b16 v[96:97], v3 offset:45056
	ds_read_b64_tr_b16 v[90:91], v98 offset:38912
	ds_read_b64_tr_b16 v[94:95], v98 offset:43008
	ds_read_b64_tr_b16 v[98:99], v98 offset:47104
	v_add3_u32 v3, v211, v210, v180
	v_mov_b32_e32 v211, v212
	s_waitcnt lgkmcnt(6)
	v_mfma_f32_32x32x16_bf16 v[32:47], v[84:87], v[4:7], v[32:47]
	s_waitcnt lgkmcnt(2)
	v_mfma_f32_32x32x16_bf16 v[32:47], v[88:91], v[8:11], v[32:47]
	s_waitcnt lgkmcnt(1)
	v_mfma_f32_32x32x16_bf16 v[32:47], v[92:95], v[12:15], v[32:47]
	s_waitcnt lgkmcnt(0)
	v_mfma_f32_32x32x16_bf16 v[32:47], v[96:99], v[80:83], v[32:47]
	ds_read_b64_tr_b16 v[86:87], v3 offset:34816
	ds_read_b64_tr_b16 v[84:85], v0 offset:32768
	ds_read_b64_tr_b16 v[88:89], v0 offset:36864
	ds_read_b64_tr_b16 v[92:93], v0 offset:40960
	ds_read_b64_tr_b16 v[96:97], v0 offset:45056
	ds_read_b64_tr_b16 v[90:91], v3 offset:38912
	ds_read_b64_tr_b16 v[94:95], v3 offset:43008
	ds_read_b64_tr_b16 v[98:99], v3 offset:47104
	s_waitcnt lgkmcnt(6)
	v_mfma_f32_32x32x16_bf16 v[16:31], v[84:87], v[4:7], v[16:31]
	s_waitcnt lgkmcnt(2)
	v_mfma_f32_32x32x16_bf16 v[16:31], v[88:91], v[8:11], v[16:31]
	s_waitcnt lgkmcnt(1)
	v_mfma_f32_32x32x16_bf16 v[16:31], v[92:95], v[12:15], v[16:31]
	s_waitcnt lgkmcnt(0)
	v_mfma_f32_32x32x16_bf16 v[16:31], v[96:99], v[80:83], v[16:31]
	s_add_i32 s59, s59, 64
	s_addk_i32 s58, 0x4000
	s_cmp_lg_u32 s56, s60
	s_cbranch_scc1 .LBB0_291
	s_nop 0
	s_nop 0
	s_nop 0
	s_nop 0
	s_nop 0
	s_nop 0
	s_nop 0
	s_nop 0
.LBB0_304:
	s_setprio 0
	v_mov_b32_e32 v0, v211
	s_nop 1
	v_permlane32_swap_b32_e32 v211, v0
	v_add_f32_e32 v0, v211, v0
	v_div_scale_f32 v2, s[2:3], v0, v0, 1.0
	v_rcp_f32_e32 v4, v2
	v_add3_u32 v8, s91, v177, v176
	v_lshlrev_b32_e32 v9, 4, v145
	s_waitcnt vmcnt(0)
	v_fma_f32 v3, -v2, v4, 1.0
	v_fmac_f32_e32 v4, v3, v4
	v_div_scale_f32 v3, vcc, 1.0, v0, 1.0
	v_mul_f32_e32 v5, v3, v4
	v_fma_f32 v6, -v2, v5, v3
	v_fmac_f32_e32 v5, v6, v4
	v_add_u32_e32 v10, v8, v9
	v_fma_f32 v6, -v2, v5, v3
	ds_read_b64 v[2:3], v10
	v_div_fmas_f32 v4, v6, v4, v5
	v_div_fixup_f32 v0, v4, v0, 1.0
	v_pk_mul_f32 v[4:5], v[64:65], v[0:1] op_sel_hi:[1,0]
	s_mulk_i32 s93, 0x1400
	s_waitcnt lgkmcnt(0)
	v_lshlrev_b32_e32 v6, 16, v2
	v_and_b32_e32 v7, 0xffff0000, v2
	v_pk_mul_f32 v[4:5], v[4:5], v[6:7]
	v_lshlrev_b32_e32 v6, 16, v3
	v_cvt_pk_bf16_f32 v2, v4, v5
	v_pk_mul_f32 v[4:5], v[66:67], v[0:1] op_sel_hi:[1,0]
	v_and_b32_e32 v7, 0xffff0000, v3
	v_pk_mul_f32 v[4:5], v[4:5], v[6:7]
	s_mul_hi_u32 s2, s92, 0x1400
	v_cvt_pk_bf16_f32 v3, v4, v5
	ds_write_b64 v10, v[2:3]
	v_xad_u32 v10, v9, 16, v8
	ds_read_b64 v[2:3], v10
	v_pk_mul_f32 v[4:5], v[68:69], v[0:1] op_sel_hi:[1,0]
	s_add_i32 s2, s2, s93
	s_mulk_i32 s92, 0x1400
	s_add_u32 s3, s30, s92
	s_waitcnt lgkmcnt(0)
	v_lshlrev_b32_e32 v6, 16, v2
	v_and_b32_e32 v7, 0xffff0000, v2
	v_pk_mul_f32 v[4:5], v[4:5], v[6:7]
	v_lshlrev_b32_e32 v6, 16, v3
	v_cvt_pk_bf16_f32 v2, v4, v5
	v_pk_mul_f32 v[4:5], v[70:71], v[0:1] op_sel_hi:[1,0]
	v_and_b32_e32 v7, 0xffff0000, v3
	v_pk_mul_f32 v[4:5], v[4:5], v[6:7]
	s_addc_u32 s20, s31, s2
	v_cvt_pk_bf16_f32 v3, v4, v5
	ds_write_b64 v10, v[2:3]
	v_xad_u32 v10, v9, 32, v8
	ds_read_b64 v[2:3], v10
	v_pk_mul_f32 v[4:5], v[72:73], v[0:1] op_sel_hi:[1,0]
	s_add_u32 s2, s3, s90
	s_addc_u32 s3, s20, 0
	v_mov_b32_e32 v145, v1
	s_waitcnt lgkmcnt(0)
	v_lshlrev_b32_e32 v6, 16, v2
	v_and_b32_e32 v7, 0xffff0000, v2
	v_pk_mul_f32 v[4:5], v[4:5], v[6:7]
	v_lshlrev_b32_e32 v6, 16, v3
	v_cvt_pk_bf16_f32 v2, v4, v5
	v_pk_mul_f32 v[4:5], v[74:75], v[0:1] op_sel_hi:[1,0]
	v_and_b32_e32 v7, 0xffff0000, v3
	v_pk_mul_f32 v[4:5], v[4:5], v[6:7]
	s_nop 0
	v_cvt_pk_bf16_f32 v3, v4, v5
	ds_write_b64 v10, v[2:3]
	v_xad_u32 v10, v9, 48, v8
	ds_read_b64 v[2:3], v10
	v_pk_mul_f32 v[4:5], v[76:77], v[0:1] op_sel_hi:[1,0]
	s_waitcnt lgkmcnt(0)
	v_lshlrev_b32_e32 v6, 16, v2
	v_and_b32_e32 v7, 0xffff0000, v2
	v_pk_mul_f32 v[4:5], v[4:5], v[6:7]
	v_lshlrev_b32_e32 v6, 16, v3
	v_cvt_pk_bf16_f32 v2, v4, v5
	v_pk_mul_f32 v[4:5], v[78:79], v[0:1] op_sel_hi:[1,0]
	v_and_b32_e32 v7, 0xffff0000, v3
	v_pk_mul_f32 v[4:5], v[4:5], v[6:7]
	s_nop 0
	v_cvt_pk_bf16_f32 v3, v4, v5
	ds_write_b64 v10, v[2:3]
	v_xad_u32 v10, v9, 64, v8
	ds_read_b64 v[2:3], v10
	v_pk_mul_f32 v[4:5], v[48:49], v[0:1] op_sel_hi:[1,0]
	s_waitcnt lgkmcnt(0)
	v_lshlrev_b32_e32 v6, 16, v2
	v_and_b32_e32 v7, 0xffff0000, v2
	v_pk_mul_f32 v[4:5], v[4:5], v[6:7]
	v_lshlrev_b32_e32 v6, 16, v3
	v_cvt_pk_bf16_f32 v2, v4, v5
	v_pk_mul_f32 v[4:5], v[50:51], v[0:1] op_sel_hi:[1,0]
	v_and_b32_e32 v7, 0xffff0000, v3
	v_pk_mul_f32 v[4:5], v[4:5], v[6:7]
	s_nop 0
	v_cvt_pk_bf16_f32 v3, v4, v5
	ds_write_b64 v10, v[2:3]
	v_xad_u32 v10, v9, s69, v8
	ds_read_b64 v[2:3], v10
	v_pk_mul_f32 v[4:5], v[52:53], v[0:1] op_sel_hi:[1,0]
	s_waitcnt lgkmcnt(0)
	v_lshlrev_b32_e32 v6, 16, v2
	v_and_b32_e32 v7, 0xffff0000, v2
	v_pk_mul_f32 v[4:5], v[4:5], v[6:7]
	v_lshlrev_b32_e32 v6, 16, v3
	v_cvt_pk_bf16_f32 v2, v4, v5
	v_pk_mul_f32 v[4:5], v[54:55], v[0:1] op_sel_hi:[1,0]
	v_and_b32_e32 v7, 0xffff0000, v3
	v_pk_mul_f32 v[4:5], v[4:5], v[6:7]
	s_nop 0
	v_cvt_pk_bf16_f32 v3, v4, v5
	ds_write_b64 v10, v[2:3]
	v_xad_u32 v10, v9, s70, v8
	ds_read_b64 v[2:3], v10
	v_pk_mul_f32 v[4:5], v[56:57], v[0:1] op_sel_hi:[1,0]
	s_waitcnt lgkmcnt(0)
	v_lshlrev_b32_e32 v6, 16, v2
	v_and_b32_e32 v7, 0xffff0000, v2
	v_pk_mul_f32 v[4:5], v[4:5], v[6:7]
	v_lshlrev_b32_e32 v6, 16, v3
	v_cvt_pk_bf16_f32 v2, v4, v5
	v_pk_mul_f32 v[4:5], v[58:59], v[0:1] op_sel_hi:[1,0]
	v_and_b32_e32 v7, 0xffff0000, v3
	v_pk_mul_f32 v[4:5], v[4:5], v[6:7]
	s_nop 0
	v_cvt_pk_bf16_f32 v3, v4, v5
	ds_write_b64 v10, v[2:3]
	v_xad_u32 v10, v9, s71, v8
	ds_read_b64 v[2:3], v10
	v_pk_mul_f32 v[4:5], v[60:61], v[0:1] op_sel_hi:[1,0]
	s_waitcnt lgkmcnt(0)
	v_lshlrev_b32_e32 v6, 16, v2
	v_and_b32_e32 v7, 0xffff0000, v2
	v_pk_mul_f32 v[4:5], v[4:5], v[6:7]
	v_lshlrev_b32_e32 v6, 16, v3
	v_cvt_pk_bf16_f32 v2, v4, v5
	v_pk_mul_f32 v[4:5], v[62:63], v[0:1] op_sel_hi:[1,0]
	v_and_b32_e32 v7, 0xffff0000, v3
	v_pk_mul_f32 v[4:5], v[4:5], v[6:7]
	s_nop 0
	v_cvt_pk_bf16_f32 v3, v4, v5
	ds_write_b64 v10, v[2:3]
	v_xad_u32 v10, v9, s72, v8
	ds_read_b64 v[2:3], v10
	v_pk_mul_f32 v[4:5], v[32:33], v[0:1] op_sel_hi:[1,0]
	s_waitcnt lgkmcnt(0)
	v_lshlrev_b32_e32 v6, 16, v2
	v_and_b32_e32 v7, 0xffff0000, v2
	v_pk_mul_f32 v[4:5], v[4:5], v[6:7]
	v_lshlrev_b32_e32 v6, 16, v3
	v_cvt_pk_bf16_f32 v2, v4, v5
	v_pk_mul_f32 v[4:5], v[34:35], v[0:1] op_sel_hi:[1,0]
	v_and_b32_e32 v7, 0xffff0000, v3
	v_pk_mul_f32 v[4:5], v[4:5], v[6:7]
	s_nop 0
	v_cvt_pk_bf16_f32 v3, v4, v5
	ds_write_b64 v10, v[2:3]
	v_xad_u32 v10, v9, s73, v8
	ds_read_b64 v[2:3], v10
	v_pk_mul_f32 v[4:5], v[36:37], v[0:1] op_sel_hi:[1,0]
	s_waitcnt lgkmcnt(0)
	v_lshlrev_b32_e32 v6, 16, v2
	v_and_b32_e32 v7, 0xffff0000, v2
	v_pk_mul_f32 v[4:5], v[4:5], v[6:7]
	v_lshlrev_b32_e32 v6, 16, v3
	v_cvt_pk_bf16_f32 v2, v4, v5
	v_pk_mul_f32 v[4:5], v[38:39], v[0:1] op_sel_hi:[1,0]
	v_and_b32_e32 v7, 0xffff0000, v3
	v_pk_mul_f32 v[4:5], v[4:5], v[6:7]
	s_nop 0
	v_cvt_pk_bf16_f32 v3, v4, v5
	ds_write_b64 v10, v[2:3]
	v_xad_u32 v10, v9, s79, v8
	ds_read_b64 v[2:3], v10
	v_pk_mul_f32 v[4:5], v[40:41], v[0:1] op_sel_hi:[1,0]
	s_waitcnt lgkmcnt(0)
	v_lshlrev_b32_e32 v6, 16, v2
	v_and_b32_e32 v7, 0xffff0000, v2
	v_pk_mul_f32 v[4:5], v[4:5], v[6:7]
	v_lshlrev_b32_e32 v6, 16, v3
	v_cvt_pk_bf16_f32 v2, v4, v5
	v_pk_mul_f32 v[4:5], v[42:43], v[0:1] op_sel_hi:[1,0]
	v_and_b32_e32 v7, 0xffff0000, v3
	v_pk_mul_f32 v[4:5], v[4:5], v[6:7]
	s_nop 0
	v_cvt_pk_bf16_f32 v3, v4, v5
	ds_write_b64 v10, v[2:3]
	v_xad_u32 v10, v9, s80, v8
	ds_read_b64 v[2:3], v10
	v_pk_mul_f32 v[4:5], v[44:45], v[0:1] op_sel_hi:[1,0]
	s_waitcnt lgkmcnt(0)
	v_lshlrev_b32_e32 v6, 16, v2
	v_and_b32_e32 v7, 0xffff0000, v2
	v_pk_mul_f32 v[4:5], v[4:5], v[6:7]
	v_lshlrev_b32_e32 v6, 16, v3
	v_cvt_pk_bf16_f32 v2, v4, v5
	v_pk_mul_f32 v[4:5], v[46:47], v[0:1] op_sel_hi:[1,0]
	v_and_b32_e32 v7, 0xffff0000, v3
	v_pk_mul_f32 v[4:5], v[4:5], v[6:7]
	s_nop 0
	v_cvt_pk_bf16_f32 v3, v4, v5
	ds_write_b64 v10, v[2:3]
	v_xad_u32 v10, v9, s81, v8
	ds_read_b64 v[2:3], v10
	v_pk_mul_f32 v[4:5], v[16:17], v[0:1] op_sel_hi:[1,0]
	s_waitcnt lgkmcnt(0)
	v_lshlrev_b32_e32 v6, 16, v2
	v_and_b32_e32 v7, 0xffff0000, v2
	v_pk_mul_f32 v[4:5], v[4:5], v[6:7]
	v_lshlrev_b32_e32 v6, 16, v3
	v_cvt_pk_bf16_f32 v2, v4, v5
	v_pk_mul_f32 v[4:5], v[18:19], v[0:1] op_sel_hi:[1,0]
	v_and_b32_e32 v7, 0xffff0000, v3
	v_pk_mul_f32 v[4:5], v[4:5], v[6:7]
	s_nop 0
	v_cvt_pk_bf16_f32 v3, v4, v5
	ds_write_b64 v10, v[2:3]
	v_xad_u32 v10, v9, s82, v8
	ds_read_b64 v[2:3], v10
	v_pk_mul_f32 v[4:5], v[20:21], v[0:1] op_sel_hi:[1,0]
	s_waitcnt lgkmcnt(0)
	v_lshlrev_b32_e32 v6, 16, v2
	v_and_b32_e32 v7, 0xffff0000, v2
	v_pk_mul_f32 v[4:5], v[4:5], v[6:7]
	v_lshlrev_b32_e32 v6, 16, v3
	v_cvt_pk_bf16_f32 v2, v4, v5
	v_pk_mul_f32 v[4:5], v[22:23], v[0:1] op_sel_hi:[1,0]
	v_and_b32_e32 v7, 0xffff0000, v3
	v_pk_mul_f32 v[4:5], v[4:5], v[6:7]
	s_nop 0
	v_cvt_pk_bf16_f32 v3, v4, v5
	ds_write_b64 v10, v[2:3]
	v_xad_u32 v10, v9, s83, v8
	ds_read_b64 v[2:3], v10
	v_pk_mul_f32 v[4:5], v[24:25], v[0:1] op_sel_hi:[1,0]
	v_xad_u32 v8, v9, s84, v8
	s_waitcnt lgkmcnt(0)
	v_lshlrev_b32_e32 v6, 16, v2
	v_and_b32_e32 v7, 0xffff0000, v2
	v_pk_mul_f32 v[4:5], v[4:5], v[6:7]
	v_lshlrev_b32_e32 v6, 16, v3
	v_cvt_pk_bf16_f32 v2, v4, v5
	v_pk_mul_f32 v[4:5], v[26:27], v[0:1] op_sel_hi:[1,0]
	v_and_b32_e32 v7, 0xffff0000, v3
	v_pk_mul_f32 v[4:5], v[4:5], v[6:7]
	s_nop 0
	v_cvt_pk_bf16_f32 v3, v4, v5
	ds_write_b64 v10, v[2:3]
	ds_read_b64 v[2:3], v8
	v_pk_mul_f32 v[4:5], v[28:29], v[0:1] op_sel_hi:[1,0]
	s_waitcnt lgkmcnt(0)
	v_lshlrev_b32_e32 v6, 16, v2
	v_and_b32_e32 v7, 0xffff0000, v2
	v_pk_mul_f32 v[4:5], v[4:5], v[6:7]
	v_lshlrev_b32_e32 v6, 16, v3
	v_cvt_pk_bf16_f32 v2, v4, v5
	v_pk_mul_f32 v[4:5], v[30:31], v[0:1] op_sel_hi:[1,0]
	v_and_b32_e32 v7, 0xffff0000, v3
	v_pk_mul_f32 v[4:5], v[4:5], v[6:7]
	v_lshlrev_b32_e32 v0, 4, v174
	v_cvt_pk_bf16_f32 v3, v4, v5
	v_and_b32_e32 v0, 0xf0, v0
	ds_write_b64 v8, v[2:3]
	v_add_u32_e32 v18, s91, v0
	s_waitcnt lgkmcnt(0)
	v_lshl_add_u32 v6, v170, 8, v18
	ds_read_b128 v[2:5], v6
	v_mul_u32_u24_e32 v0, 0x1400, v170
	v_lshl_add_u64 v[14:15], s[2:3], 0, v[0:1]
	v_lshl_add_u64 v[10:11], v[14:15], 0, v[144:145]
	v_lshl_add_u32 v0, v147, 8, v18
	v_mov_b32_e32 v147, v1
	s_waitcnt lgkmcnt(0)
	global_store_dwordx4 v[10:11], v[2:5], off
	v_lshl_add_u64 v[10:11], v[14:15], 0, v[146:147]
	ds_read_b128 v[6:9], v6 offset:4096
	ds_read_b128 v[2:5], v0
	v_add_co_u32_e32 v16, vcc, s86, v10
	v_lshl_add_u32 v0, v149, 8, v18
	s_nop 0
	v_addc_co_u32_e32 v17, vcc, 0, v11, vcc
	ds_read_b128 v[10:13], v0
	v_lshl_add_u64 v[14:15], v[14:15], 0, s[48:49]
	v_mov_b32_e32 v149, v1
	s_waitcnt lgkmcnt(0)
	global_store_dwordx4 v[16:17], v[2:5], off
	v_lshl_add_u32 v0, v153, 8, v18
	v_mov_b32_e32 v153, v1
	v_lshl_add_u64 v[2:3], v[14:15], 0, v[148:149]
	global_store_dwordx4 v[2:3], v[10:13], off
	ds_read_b128 v[2:5], v0
	v_lshl_add_u32 v0, v151, 8, v18
	v_lshl_add_u64 v[10:11], v[14:15], 0, v[152:153]
	v_add_co_u32_e32 v14, vcc, s86, v10
	v_mov_b32_e32 v151, v1
	s_nop 0
	v_addc_co_u32_e32 v15, vcc, 0, v11, vcc
	ds_read_b128 v[10:13], v0
	v_mad_u32_u24 v0, v170, s85, v196
	s_waitcnt lgkmcnt(0)
	global_store_dwordx4 v[14:15], v[2:5], off
	s_nop 1
	v_lshl_add_u64 v[2:3], s[2:3], 0, v[0:1]
	v_lshl_add_u64 v[2:3], v[2:3], 0, v[144:145]
	v_mad_u32_u24 v0, v170, s85, v197
	global_store_dwordx4 v[2:3], v[6:9], off
	v_lshl_add_u64 v[2:3], s[2:3], 0, v[0:1]
	v_lshl_add_u64 v[2:3], v[2:3], 0, v[150:151]
	v_lshl_add_u32 v0, v155, 8, v18
	global_store_dwordx4 v[2:3], v[10:13], off
	ds_read_b128 v[2:5], v0
	v_mad_u32_u24 v0, v170, s85, v198
	v_lshl_add_u64 v[6:7], s[2:3], 0, v[0:1]
	v_mov_b32_e32 v155, v1
	v_lshl_add_u32 v0, v157, 8, v18
	v_lshl_add_u64 v[10:11], v[6:7], 0, v[154:155]
	ds_read_b128 v[6:9], v0
	v_mad_u32_u24 v0, v170, s85, v199
	s_waitcnt lgkmcnt(0)
	global_store_dwordx4 v[10:11], v[2:5], off
	v_mov_b32_e32 v157, v1
	s_nop 0
	v_lshl_add_u64 v[2:3], s[2:3], 0, v[0:1]
	v_lshl_add_u64 v[2:3], v[2:3], 0, v[156:157]
	global_store_dwordx4 v[2:3], v[6:9], off
	s_waitcnt lgkmcnt(0)
	s_mov_b64 s[2:3], 0

.LBB0_421:
	v_lshlrev_b32_e32 v0, 3, v74
	v_lshlrev_b32_e32 v3, 3, v5
	v_lshl_add_u64 v[164:165], v[0:1], 1, s[52:53]
	v_lshlrev_b32_e32 v0, 1, v3
	v_and_b32_e32 v174, 63, v2
	v_mov_b32_e32 v5, v1
	v_lshl_add_u64 v[168:169], s[52:53], 0, v[0:1]
	v_lshlrev_b32_e32 v180, 2, v72
	v_bfe_u32 v0, v2, 2, 2
	v_lshrrev_b32_e32 v3, 3, v2
	v_bfe_u32 v2, v2, 1, 1
	v_lshl_add_u64 v[162:163], s[54:55], 0, v[4:5]
	v_and_or_b32 v2, v3, 2, v2
	v_lshlrev_b32_e32 v3, 2, v0
	v_lshlrev_b32_e32 v5, 3, v174
	v_or_b32_e32 v0, v180, v0
	v_or_b32_e32 v4, v3, v72
	v_and_b32_e32 v181, 8, v5
	v_xor_b32_e32 v5, v72, v145
	v_lshlrev_b32_e32 v203, 8, v0
	v_bitop3_b32 v0, v3, v2, v72 bitop3:0x36
	v_lshlrev_b32_e32 v182, 4, v5
	v_bitop3_b32 v5, v72, v145, 2 bitop3:0x36
	v_lshlrev_b32_e32 v204, 4, v0
	v_bitop3_b32 v0, v4, v2, 2 bitop3:0x36
	v_lshlrev_b32_e32 v183, 4, v5
	v_bitop3_b32 v5, v72, v145, 4 bitop3:0x36
	v_lshlrev_b32_e32 v205, 4, v0
	v_or_b32_e32 v0, 4, v2
	v_lshlrev_b32_e32 v184, 4, v5
	v_bitop3_b32 v5, v72, v145, 6 bitop3:0x36
	v_bitop3_b32 v0, v4, v0, 2 bitop3:0x36
	v_lshlrev_b32_e32 v185, 4, v5
	v_bitop3_b32 v5, v72, v145, 8 bitop3:0x36
	v_lshlrev_b32_e32 v207, 4, v0
	v_or_b32_e32 v0, 8, v2
	v_lshlrev_b32_e32 v186, 4, v5
	v_bitop3_b32 v5, v72, v145, 10 bitop3:0x36
	v_bitop3_b32 v0, v4, v0, 2 bitop3:0x36
	v_lshlrev_b32_e32 v200, 4, v5
	v_bitop3_b32 v5, v72, v145, 12 bitop3:0x36
	v_bitop3_b32 v3, v2, v4, 4 bitop3:0x36
	v_lshlrev_b32_e32 v209, 4, v0
	v_or_b32_e32 v0, 12, v2
	v_mov_b32_e32 v7, v1
	v_lshlrev_b32_e32 v201, 4, v5
	v_bitop3_b32 v5, v72, v145, 14 bitop3:0x36
	v_lshlrev_b32_e32 v206, 4, v3
	v_bitop3_b32 v3, v2, v4, 8 bitop3:0x36
	v_bitop3_b32 v2, v2, v4, 12 bitop3:0x36
	v_bitop3_b32 v0, v4, v0, 2 bitop3:0x36
	v_mov_b32_e32 v14, v1
	v_mov_b32_e32 v15, v1
	v_lshlrev_b32_e32 v176, 3, v72
	s_lshl_b32 s56, s94, 2
	v_lshl_add_u64 v[166:167], s[54:55], 0, v[6:7]
	v_lshlrev_b32_e32 v178, 8, v73
	v_lshlrev_b32_e32 v202, 4, v5
	v_lshlrev_b32_e32 v208, 4, v3
	v_lshlrev_b32_e32 v210, 4, v2
	v_lshlrev_b32_e32 v211, 4, v0
	v_mov_b32_e32 v0, v1
	v_mov_b32_e32 v2, v1
	v_mov_b32_e32 v3, v1
	v_mov_b32_e32 v4, v1
	v_mov_b32_e32 v5, v1
	v_mov_b32_e32 v6, v1
	v_mov_b32_e32 v8, v1
	v_mov_b32_e32 v9, v1
	v_mov_b32_e32 v10, v1
	v_mov_b32_e32 v11, v1
	v_mov_b32_e32 v12, v1
	v_mov_b32_e32 v13, v1
	v_mov_b64_e32 v[30:31], v[14:15]
	v_mov_b64_e32 v[46:47], v[14:15]
	v_mov_b64_e32 v[62:63], v[14:15]
	v_mov_b64_e32 v[78:79], v[14:15]
	v_or_b32_e32 v147, 4, v170
	v_or_b32_e32 v149, 8, v170
	v_or_b32_e32 v153, 12, v170
	v_or_b32_e32 v151, 20, v170
	v_or_b32_e32 v155, 24, v170
	v_or_b32_e32 v157, 28, v170
	s_add_i32 s56, s56, 4
	s_or_b32 s54, s95, 31
	v_add_u32_e32 v179, 0, v178
	s_mov_b32 s55, 0
	v_mov_b32_e32 v212, 0
	v_mov_b32_e32 v213, 0xf149f2ca
	s_mov_b32 s57, 0
	v_mov_b64_e32 v[28:29], v[12:13]
	v_mov_b64_e32 v[26:27], v[10:11]
	v_mov_b64_e32 v[24:25], v[8:9]
	v_mov_b64_e32 v[22:23], v[6:7]
	v_mov_b64_e32 v[20:21], v[4:5]
	v_mov_b64_e32 v[18:19], v[2:3]
	v_mov_b64_e32 v[16:17], v[0:1]
	v_mov_b64_e32 v[44:45], v[12:13]
	v_mov_b64_e32 v[42:43], v[10:11]
	v_mov_b64_e32 v[40:41], v[8:9]
	v_mov_b64_e32 v[38:39], v[6:7]
	v_mov_b64_e32 v[36:37], v[4:5]
	v_mov_b64_e32 v[34:35], v[2:3]
	v_mov_b64_e32 v[32:33], v[0:1]
	v_mov_b64_e32 v[60:61], v[12:13]
	v_mov_b64_e32 v[58:59], v[10:11]
	v_mov_b64_e32 v[56:57], v[8:9]
	v_mov_b64_e32 v[54:55], v[6:7]
	v_mov_b64_e32 v[52:53], v[4:5]
	v_mov_b64_e32 v[50:51], v[2:3]
	v_mov_b64_e32 v[48:49], v[0:1]
	v_mov_b64_e32 v[76:77], v[12:13]
	v_mov_b64_e32 v[74:75], v[10:11]
	v_mov_b64_e32 v[72:73], v[8:9]
	v_mov_b64_e32 v[70:71], v[6:7]
	v_mov_b64_e32 v[68:69], v[4:5]
	v_mov_b64_e32 v[66:67], v[2:3]
	v_mov_b64_e32 v[64:65], v[0:1]
	s_mov_b32 s59, 0
	s_cmp_lt_u32 s92, 0x2000
	s_cbranch_scc1 .Lsprio2
	s_setprio 1

.LBB0_433:
	s_nop 0
	s_nop 8
	v_max_f32_e32 v0, v97, v97
	v_max_f32_e32 v2, v96, v96
	v_max_f32_e32 v0, v2, v0
	v_max3_f32 v0, v0, v98, v99
	v_max3_f32 v0, v0, v100, v101
	v_max3_f32 v0, v0, v102, v103
	v_max3_f32 v0, v0, v104, v105
	v_max3_f32 v0, v0, v106, v107
	v_max3_f32 v0, v0, v108, v109
	v_max3_f32 v0, v0, v110, v111
	v_max3_f32 v0, v0, v80, v81
	v_max3_f32 v0, v0, v82, v83
	v_max3_f32 v0, v0, v84, v85
	v_max3_f32 v0, v0, v86, v87
	v_max3_f32 v0, v0, v88, v89
	v_max3_f32 v0, v0, v90, v91
	v_max3_f32 v0, v0, v92, v93
	v_max3_f32 v0, v0, v94, v95
	v_mov_b32_e32 v2, v0
	s_nop 1
	v_permlane32_swap_b32_e32 v0, v2
	v_max3_f32 v2, v213, v0, v2
	v_sub_f32_e32 v0, v213, v2
	v_exp_f32_e32 v0, v0
	s_nop 0
	v_cmp_neq_f32_e32 vcc, 1.0, v0
	s_cbranch_vccz .LBB0_435
	v_pk_mul_f32 v[78:79], v[78:79], v[0:1] op_sel_hi:[1,0]
	v_pk_mul_f32 v[76:77], v[76:77], v[0:1] op_sel_hi:[1,0]
	v_pk_mul_f32 v[74:75], v[74:75], v[0:1] op_sel_hi:[1,0]
	v_pk_mul_f32 v[72:73], v[72:73], v[0:1] op_sel_hi:[1,0]
	v_pk_mul_f32 v[70:71], v[70:71], v[0:1] op_sel_hi:[1,0]
	v_pk_mul_f32 v[68:69], v[68:69], v[0:1] op_sel_hi:[1,0]
	v_pk_mul_f32 v[66:67], v[66:67], v[0:1] op_sel_hi:[1,0]
	v_pk_mul_f32 v[64:65], v[64:65], v[0:1] op_sel_hi:[1,0]
	v_pk_mul_f32 v[62:63], v[62:63], v[0:1] op_sel_hi:[1,0]
	v_pk_mul_f32 v[60:61], v[60:61], v[0:1] op_sel_hi:[1,0]
	v_pk_mul_f32 v[58:59], v[58:59], v[0:1] op_sel_hi:[1,0]
	v_pk_mul_f32 v[56:57], v[56:57], v[0:1] op_sel_hi:[1,0]
	v_pk_mul_f32 v[54:55], v[54:55], v[0:1] op_sel_hi:[1,0]
	v_pk_mul_f32 v[52:53], v[52:53], v[0:1] op_sel_hi:[1,0]
	v_pk_mul_f32 v[50:51], v[50:51], v[0:1] op_sel_hi:[1,0]
	v_pk_mul_f32 v[48:49], v[48:49], v[0:1] op_sel_hi:[1,0]
	v_pk_mul_f32 v[46:47], v[46:47], v[0:1] op_sel_hi:[1,0]
	v_pk_mul_f32 v[44:45], v[44:45], v[0:1] op_sel_hi:[1,0]
	v_pk_mul_f32 v[42:43], v[42:43], v[0:1] op_sel_hi:[1,0]
	v_pk_mul_f32 v[40:41], v[40:41], v[0:1] op_sel_hi:[1,0]
	v_pk_mul_f32 v[38:39], v[38:39], v[0:1] op_sel_hi:[1,0]
	v_pk_mul_f32 v[36:37], v[36:37], v[0:1] op_sel_hi:[1,0]
	v_pk_mul_f32 v[34:35], v[34:35], v[0:1] op_sel_hi:[1,0]
	v_pk_mul_f32 v[32:33], v[32:33], v[0:1] op_sel_hi:[1,0]
	v_pk_mul_f32 v[30:31], v[30:31], v[0:1] op_sel_hi:[1,0]
	v_pk_mul_f32 v[28:29], v[28:29], v[0:1] op_sel_hi:[1,0]
	v_pk_mul_f32 v[26:27], v[26:27], v[0:1] op_sel_hi:[1,0]
	v_pk_mul_f32 v[24:25], v[24:25], v[0:1] op_sel_hi:[1,0]
	v_pk_mul_f32 v[22:23], v[22:23], v[0:1] op_sel_hi:[1,0]
	v_pk_mul_f32 v[20:21], v[20:21], v[0:1] op_sel_hi:[1,0]
	v_pk_mul_f32 v[18:19], v[18:19], v[0:1] op_sel_hi:[1,0]
	v_pk_mul_f32 v[16:17], v[16:17], v[0:1] op_sel_hi:[1,0]
.LBB0_435:
	v_sub_f32_e32 v8, v82, v2
	v_sub_f32_e32 v9, v83, v2
	v_sub_f32_e32 v7, v98, v2
	v_exp_f32_e32 v98, v8
	v_sub_f32_e32 v8, v99, v2
	v_exp_f32_e32 v99, v9
	v_sub_f32_e32 v9, v100, v2
	v_exp_f32_e32 v12, v9
	v_sub_f32_e32 v9, v84, v2
	v_exp_f32_e32 v100, v9
	v_sub_f32_e32 v9, v101, v2
	v_exp_f32_e32 v13, v9
	v_sub_f32_e32 v9, v85, v2
	v_exp_f32_e32 v101, v9
	v_sub_f32_e32 v9, v102, v2
	v_exp_f32_e32 v14, v9
	v_sub_f32_e32 v9, v86, v2
	v_exp_f32_e32 v102, v9
	v_sub_f32_e32 v9, v103, v2
	v_exp_f32_e32 v15, v9
	v_sub_f32_e32 v9, v87, v2
	v_sub_f32_e32 v3, v96, v2
	v_sub_f32_e32 v4, v80, v2
	v_exp_f32_e32 v103, v9
	v_sub_f32_e32 v9, v104, v2
	v_exp_f32_e32 v3, v3
	v_exp_f32_e32 v96, v4
	v_sub_f32_e32 v4, v97, v2
	v_sub_f32_e32 v5, v81, v2
	v_exp_f32_e32 v104, v9
	v_sub_f32_e32 v9, v88, v2
	v_exp_f32_e32 v4, v4
	v_exp_f32_e32 v97, v5
	v_exp_f32_e32 v88, v9
	v_sub_f32_e32 v9, v105, v2
	v_exp_f32_e32 v7, v7
	v_exp_f32_e32 v105, v9
	v_sub_f32_e32 v9, v89, v2
	v_exp_f32_e32 v8, v8
	v_exp_f32_e32 v89, v9
	v_sub_f32_e32 v9, v106, v2
	v_add_f32_e32 v5, v3, v96
	v_exp_f32_e32 v106, v9
	v_sub_f32_e32 v9, v90, v2
	v_add_f32_e32 v5, 0, v5
	v_add_f32_e32 v6, v4, v97
	v_exp_f32_e32 v90, v9
	v_sub_f32_e32 v9, v107, v2
	v_add_f32_e32 v5, v6, v5
	v_add_f32_e32 v6, v7, v98
	v_exp_f32_e32 v107, v9
	v_sub_f32_e32 v9, v91, v2
	v_add_f32_e32 v5, v6, v5
	v_add_f32_e32 v6, v8, v99
	v_exp_f32_e32 v91, v9
	v_sub_f32_e32 v9, v108, v2
	v_add_f32_e32 v5, v6, v5
	v_add_f32_e32 v6, v12, v100
	v_exp_f32_e32 v108, v9
	v_sub_f32_e32 v9, v92, v2
	v_add_f32_e32 v5, v6, v5
	v_add_f32_e32 v6, v13, v101
	v_exp_f32_e32 v92, v9
	v_sub_f32_e32 v9, v109, v2
	v_add_f32_e32 v5, v6, v5
	v_add_f32_e32 v6, v14, v102
	v_exp_f32_e32 v109, v9
	v_sub_f32_e32 v9, v93, v2
	v_add_f32_e32 v5, v6, v5
	v_add_f32_e32 v6, v15, v103
	v_exp_f32_e32 v93, v9
	v_sub_f32_e32 v9, v110, v2
	v_add_f32_e32 v5, v6, v5
	v_add_f32_e32 v6, v104, v88
	v_exp_f32_e32 v110, v9
	v_sub_f32_e32 v9, v94, v2
	v_add_f32_e32 v5, v6, v5
	v_add_f32_e32 v6, v105, v89
	v_exp_f32_e32 v94, v9
	v_sub_f32_e32 v9, v111, v2
	v_add_f32_e32 v5, v6, v5
	v_add_f32_e32 v6, v106, v90
	v_exp_f32_e32 v111, v9
	v_sub_f32_e32 v9, v95, v2
	v_add_f32_e32 v5, v6, v5
	v_add_f32_e32 v6, v107, v91
	v_exp_f32_e32 v95, v9
	v_add_f32_e32 v5, v6, v5
	v_add_f32_e32 v6, v108, v92
	v_add_f32_e32 v5, v6, v5
	v_add_f32_e32 v6, v109, v93
	v_add_f32_e32 v5, v6, v5
	v_add_f32_e32 v6, v110, v94
	v_add_f32_e32 v5, v6, v5
	v_add_f32_e32 v6, v111, v95
	v_add_f32_e32 v213, v6, v5
	v_fmac_f32_e32 v213, v212, v0
	s_add_i32 s0, s2, 0
	s_nop 0
	v_add_u32_e32 v0, s0, v181
	v_add_u32_e32 v212, s0, v203
	v_cvt_pk_bf16_f32 v4, v3, v4
	v_add3_u32 v3, v0, v204, v203
	v_add3_u32 v86, v212, v205, v181
	v_cvt_pk_bf16_f32 v5, v7, v8
	s_nop 0
	ds_read_b64_tr_b16 v[8:9], v3 offset:32768
	ds_read_b64_tr_b16 v[10:11], v86 offset:34816
	v_cvt_pk_bf16_f32 v6, v12, v13
	v_cvt_pk_bf16_f32 v7, v14, v15
	ds_read_b64_tr_b16 v[12:13], v3 offset:36864
	ds_read_b64_tr_b16 v[80:81], v3 offset:40960
	ds_read_b64_tr_b16 v[84:85], v3 offset:45056
	ds_read_b64_tr_b16 v[14:15], v86 offset:38912
	ds_read_b64_tr_b16 v[82:83], v86 offset:43008
	ds_read_b64_tr_b16 v[86:87], v86 offset:47104
	s_waitcnt lgkmcnt(6)
	v_mfma_f32_32x32x16_bf16 v[64:79], v[8:11], v[4:7], v[64:79]
	v_cvt_pk_bf16_f32 v8, v104, v105
	v_cvt_pk_bf16_f32 v9, v106, v107
	v_cvt_pk_bf16_f32 v10, v108, v109
	v_cvt_pk_bf16_f32 v11, v110, v111
	v_add3_u32 v3, v0, v206, v203
	s_waitcnt lgkmcnt(2)
	v_mfma_f32_32x32x16_bf16 v[64:79], v[12:15], v[8:11], v[64:79]
	v_cvt_pk_bf16_f32 v12, v96, v97
	v_cvt_pk_bf16_f32 v13, v98, v99
	v_cvt_pk_bf16_f32 v14, v100, v101
	v_cvt_pk_bf16_f32 v15, v102, v103
	v_add3_u32 v100, v212, v207, v181
	s_waitcnt lgkmcnt(1)
	v_mfma_f32_32x32x16_bf16 v[64:79], v[80:83], v[12:15], v[64:79]
	v_cvt_pk_bf16_f32 v80, v88, v89
	ds_read_b64_tr_b16 v[88:89], v100 offset:34816
	v_cvt_pk_bf16_f32 v81, v90, v91
	v_cvt_pk_bf16_f32 v82, v92, v93
	v_cvt_pk_bf16_f32 v83, v94, v95
	s_waitcnt lgkmcnt(1)
	s_nop 0
	v_mfma_f32_32x32x16_bf16 v[64:79], v[84:87], v[80:83], v[64:79]
	ds_read_b64_tr_b16 v[86:87], v3 offset:32768
	ds_read_b64_tr_b16 v[90:91], v3 offset:36864
	ds_read_b64_tr_b16 v[94:95], v3 offset:40960
	ds_read_b64_tr_b16 v[98:99], v3 offset:45056
	ds_read_b64_tr_b16 v[92:93], v100 offset:38912
	ds_read_b64_tr_b16 v[96:97], v100 offset:43008
	ds_read_b64_tr_b16 v[100:101], v100 offset:47104
	v_add3_u32 v3, v0, v208, v203
	v_add3_u32 v0, v0, v210, v203
	s_waitcnt lgkmcnt(6)
	v_mfma_f32_32x32x16_bf16 v[48:63], v[86:89], v[4:7], v[48:63]
	s_waitcnt lgkmcnt(2)
	v_mfma_f32_32x32x16_bf16 v[48:63], v[90:93], v[8:11], v[48:63]
	s_waitcnt lgkmcnt(1)
	v_mfma_f32_32x32x16_bf16 v[48:63], v[94:97], v[12:15], v[48:63]
	s_waitcnt lgkmcnt(0)
	v_mfma_f32_32x32x16_bf16 v[48:63], v[98:101], v[80:83], v[48:63]
	v_add3_u32 v98, v212, v209, v181
	ds_read_b64_tr_b16 v[86:87], v98 offset:34816
	ds_read_b64_tr_b16 v[84:85], v3 offset:32768
	ds_read_b64_tr_b16 v[88:89], v3 offset:36864
	ds_read_b64_tr_b16 v[92:93], v3 offset:40960
	ds_read_b64_tr_b16 v[96:97], v3 offset:45056
	ds_read_b64_tr_b16 v[90:91], v98 offset:38912
	ds_read_b64_tr_b16 v[94:95], v98 offset:43008
	ds_read_b64_tr_b16 v[98:99], v98 offset:47104
	v_add3_u32 v3, v212, v211, v181
	v_mov_b32_e32 v212, v213
	s_waitcnt lgkmcnt(6)
	v_mfma_f32_32x32x16_bf16 v[32:47], v[84:87], v[4:7], v[32:47]
	s_waitcnt lgkmcnt(2)
	v_mfma_f32_32x32x16_bf16 v[32:47], v[88:91], v[8:11], v[32:47]
	s_waitcnt lgkmcnt(1)
	v_mfma_f32_32x32x16_bf16 v[32:47], v[92:95], v[12:15], v[32:47]
	s_waitcnt lgkmcnt(0)
	v_mfma_f32_32x32x16_bf16 v[32:47], v[96:99], v[80:83], v[32:47]
	ds_read_b64_tr_b16 v[86:87], v3 offset:34816
	ds_read_b64_tr_b16 v[84:85], v0 offset:32768
	ds_read_b64_tr_b16 v[88:89], v0 offset:36864
	ds_read_b64_tr_b16 v[92:93], v0 offset:40960
	ds_read_b64_tr_b16 v[96:97], v0 offset:45056
	ds_read_b64_tr_b16 v[90:91], v3 offset:38912
	ds_read_b64_tr_b16 v[94:95], v3 offset:43008
	ds_read_b64_tr_b16 v[98:99], v3 offset:47104
	s_waitcnt lgkmcnt(6)
	v_mfma_f32_32x32x16_bf16 v[16:31], v[84:87], v[4:7], v[16:31]
	s_waitcnt lgkmcnt(2)
	v_mfma_f32_32x32x16_bf16 v[16:31], v[88:91], v[8:11], v[16:31]
	s_waitcnt lgkmcnt(1)
	v_mfma_f32_32x32x16_bf16 v[16:31], v[92:95], v[12:15], v[16:31]
	s_waitcnt lgkmcnt(0)
	v_mfma_f32_32x32x16_bf16 v[16:31], v[96:99], v[80:83], v[16:31]
	s_add_i32 s57, s57, 64
	s_addk_i32 s55, 0x4000
	s_cmp_lg_u32 s56, s58
	s_cbranch_scc1 .LBB0_423
	s_nop 0
	s_nop 0
	s_nop 0
	s_nop 0
	s_nop 0
	s_nop 0
	s_nop 0
	s_nop 0
.LBB0_436:
	s_setprio 0
	v_mov_b32_e32 v0, v212
	s_nop 1
	v_permlane32_swap_b32_e32 v212, v0
	v_add_f32_e32 v0, v212, v0
	v_div_scale_f32 v2, s[0:1], v0, v0, 1.0
	v_rcp_f32_e32 v4, v2
	v_add3_u32 v8, s61, v178, v176
	v_lshlrev_b32_e32 v9, 4, v145
	s_waitcnt vmcnt(0)
	v_fma_f32 v3, -v2, v4, 1.0
	v_fmac_f32_e32 v4, v3, v4
	v_div_scale_f32 v3, vcc, 1.0, v0, 1.0
	v_mul_f32_e32 v5, v3, v4
	v_fma_f32 v6, -v2, v5, v3
	v_fmac_f32_e32 v5, v6, v4
	v_add_u32_e32 v10, v8, v9
	v_fma_f32 v6, -v2, v5, v3
	ds_read_b64 v[2:3], v10
	v_div_fmas_f32 v4, v6, v4, v5
	v_div_fixup_f32 v0, v4, v0, 1.0
	v_pk_mul_f32 v[4:5], v[64:65], v[0:1] op_sel_hi:[1,0]
	s_mulk_i32 s91, 0x1400
	s_waitcnt lgkmcnt(0)
	v_lshlrev_b32_e32 v6, 16, v2
	v_and_b32_e32 v7, 0xffff0000, v2
	v_pk_mul_f32 v[4:5], v[4:5], v[6:7]
	v_lshlrev_b32_e32 v6, 16, v3
	v_cvt_pk_bf16_f32 v2, v4, v5
	v_pk_mul_f32 v[4:5], v[66:67], v[0:1] op_sel_hi:[1,0]
	v_and_b32_e32 v7, 0xffff0000, v3
	v_pk_mul_f32 v[4:5], v[4:5], v[6:7]
	s_mul_hi_u32 s0, s90, 0x1400
	v_cvt_pk_bf16_f32 v3, v4, v5
	ds_write_b64 v10, v[2:3]
	v_xad_u32 v10, v9, 16, v8
	ds_read_b64 v[2:3], v10
	v_pk_mul_f32 v[4:5], v[68:69], v[0:1] op_sel_hi:[1,0]
	s_add_i32 s0, s0, s91
	s_mulk_i32 s90, 0x1400
	s_add_u32 s1, s30, s90
	s_waitcnt lgkmcnt(0)
	v_lshlrev_b32_e32 v6, 16, v2
	v_and_b32_e32 v7, 0xffff0000, v2
	v_pk_mul_f32 v[4:5], v[4:5], v[6:7]
	v_lshlrev_b32_e32 v6, 16, v3
	v_cvt_pk_bf16_f32 v2, v4, v5
	v_pk_mul_f32 v[4:5], v[70:71], v[0:1] op_sel_hi:[1,0]
	v_and_b32_e32 v7, 0xffff0000, v3
	v_pk_mul_f32 v[4:5], v[4:5], v[6:7]
	s_addc_u32 s2, s31, s0
	v_cvt_pk_bf16_f32 v3, v4, v5
	ds_write_b64 v10, v[2:3]
	v_xad_u32 v10, v9, 32, v8
	ds_read_b64 v[2:3], v10
	v_pk_mul_f32 v[4:5], v[72:73], v[0:1] op_sel_hi:[1,0]
	s_add_u32 s0, s1, s60
	s_addc_u32 s1, s2, 0
	v_mov_b32_e32 v145, v1
	s_waitcnt lgkmcnt(0)
	v_lshlrev_b32_e32 v6, 16, v2
	v_and_b32_e32 v7, 0xffff0000, v2
	v_pk_mul_f32 v[4:5], v[4:5], v[6:7]
	v_lshlrev_b32_e32 v6, 16, v3
	v_cvt_pk_bf16_f32 v2, v4, v5
	v_pk_mul_f32 v[4:5], v[74:75], v[0:1] op_sel_hi:[1,0]
	v_and_b32_e32 v7, 0xffff0000, v3
	v_pk_mul_f32 v[4:5], v[4:5], v[6:7]
	s_mov_b64 s[2:3], s[22:23]
	v_cvt_pk_bf16_f32 v3, v4, v5
	ds_write_b64 v10, v[2:3]
	v_xad_u32 v10, v9, 48, v8
	ds_read_b64 v[2:3], v10
	v_pk_mul_f32 v[4:5], v[76:77], v[0:1] op_sel_hi:[1,0]
	s_waitcnt lgkmcnt(0)
	v_lshlrev_b32_e32 v6, 16, v2
	v_and_b32_e32 v7, 0xffff0000, v2
	v_pk_mul_f32 v[4:5], v[4:5], v[6:7]
	v_lshlrev_b32_e32 v6, 16, v3
	v_cvt_pk_bf16_f32 v2, v4, v5
	v_pk_mul_f32 v[4:5], v[78:79], v[0:1] op_sel_hi:[1,0]
	v_and_b32_e32 v7, 0xffff0000, v3
	v_pk_mul_f32 v[4:5], v[4:5], v[6:7]
	s_nop 0
	v_cvt_pk_bf16_f32 v3, v4, v5
	ds_write_b64 v10, v[2:3]
	v_xad_u32 v10, v9, 64, v8
	ds_read_b64 v[2:3], v10
	v_pk_mul_f32 v[4:5], v[48:49], v[0:1] op_sel_hi:[1,0]
	s_waitcnt lgkmcnt(0)
	v_lshlrev_b32_e32 v6, 16, v2
	v_and_b32_e32 v7, 0xffff0000, v2
	v_pk_mul_f32 v[4:5], v[4:5], v[6:7]
	v_lshlrev_b32_e32 v6, 16, v3
	v_cvt_pk_bf16_f32 v2, v4, v5
	v_pk_mul_f32 v[4:5], v[50:51], v[0:1] op_sel_hi:[1,0]
	v_and_b32_e32 v7, 0xffff0000, v3
	v_pk_mul_f32 v[4:5], v[4:5], v[6:7]
	s_nop 0
	v_cvt_pk_bf16_f32 v3, v4, v5
	ds_write_b64 v10, v[2:3]
	v_xad_u32 v10, v9, s69, v8
	ds_read_b64 v[2:3], v10
	v_pk_mul_f32 v[4:5], v[52:53], v[0:1] op_sel_hi:[1,0]
	s_waitcnt lgkmcnt(0)
	v_lshlrev_b32_e32 v6, 16, v2
	v_and_b32_e32 v7, 0xffff0000, v2
	v_pk_mul_f32 v[4:5], v[4:5], v[6:7]
	v_lshlrev_b32_e32 v6, 16, v3
	v_cvt_pk_bf16_f32 v2, v4, v5
	v_pk_mul_f32 v[4:5], v[54:55], v[0:1] op_sel_hi:[1,0]
	v_and_b32_e32 v7, 0xffff0000, v3
	v_pk_mul_f32 v[4:5], v[4:5], v[6:7]
	s_nop 0
	v_cvt_pk_bf16_f32 v3, v4, v5
	ds_write_b64 v10, v[2:3]
	v_xad_u32 v10, v9, s70, v8
	ds_read_b64 v[2:3], v10
	v_pk_mul_f32 v[4:5], v[56:57], v[0:1] op_sel_hi:[1,0]
	s_waitcnt lgkmcnt(0)
	v_lshlrev_b32_e32 v6, 16, v2
	v_and_b32_e32 v7, 0xffff0000, v2
	v_pk_mul_f32 v[4:5], v[4:5], v[6:7]
	v_lshlrev_b32_e32 v6, 16, v3
	v_cvt_pk_bf16_f32 v2, v4, v5
	v_pk_mul_f32 v[4:5], v[58:59], v[0:1] op_sel_hi:[1,0]
	v_and_b32_e32 v7, 0xffff0000, v3
	v_pk_mul_f32 v[4:5], v[4:5], v[6:7]
	s_nop 0
	v_cvt_pk_bf16_f32 v3, v4, v5
	ds_write_b64 v10, v[2:3]
	v_xad_u32 v10, v9, s71, v8
	ds_read_b64 v[2:3], v10
	v_pk_mul_f32 v[4:5], v[60:61], v[0:1] op_sel_hi:[1,0]
	s_waitcnt lgkmcnt(0)
	v_lshlrev_b32_e32 v6, 16, v2
	v_and_b32_e32 v7, 0xffff0000, v2
	v_pk_mul_f32 v[4:5], v[4:5], v[6:7]
	v_lshlrev_b32_e32 v6, 16, v3
	v_cvt_pk_bf16_f32 v2, v4, v5
	v_pk_mul_f32 v[4:5], v[62:63], v[0:1] op_sel_hi:[1,0]
	v_and_b32_e32 v7, 0xffff0000, v3
	v_pk_mul_f32 v[4:5], v[4:5], v[6:7]
	s_nop 0
	v_cvt_pk_bf16_f32 v3, v4, v5
	ds_write_b64 v10, v[2:3]
	v_xad_u32 v10, v9, s72, v8
	ds_read_b64 v[2:3], v10
	v_pk_mul_f32 v[4:5], v[32:33], v[0:1] op_sel_hi:[1,0]
	s_waitcnt lgkmcnt(0)
	v_lshlrev_b32_e32 v6, 16, v2
	v_and_b32_e32 v7, 0xffff0000, v2
	v_pk_mul_f32 v[4:5], v[4:5], v[6:7]
	v_lshlrev_b32_e32 v6, 16, v3
	v_cvt_pk_bf16_f32 v2, v4, v5
	v_pk_mul_f32 v[4:5], v[34:35], v[0:1] op_sel_hi:[1,0]
	v_and_b32_e32 v7, 0xffff0000, v3
	v_pk_mul_f32 v[4:5], v[4:5], v[6:7]
	s_nop 0
	v_cvt_pk_bf16_f32 v3, v4, v5
	ds_write_b64 v10, v[2:3]
	v_xad_u32 v10, v9, s73, v8
	ds_read_b64 v[2:3], v10
	v_pk_mul_f32 v[4:5], v[36:37], v[0:1] op_sel_hi:[1,0]
	s_waitcnt lgkmcnt(0)
	v_lshlrev_b32_e32 v6, 16, v2
	v_and_b32_e32 v7, 0xffff0000, v2
	v_pk_mul_f32 v[4:5], v[4:5], v[6:7]
	v_lshlrev_b32_e32 v6, 16, v3
	v_cvt_pk_bf16_f32 v2, v4, v5
	v_pk_mul_f32 v[4:5], v[38:39], v[0:1] op_sel_hi:[1,0]
	v_and_b32_e32 v7, 0xffff0000, v3
	v_pk_mul_f32 v[4:5], v[4:5], v[6:7]
	s_nop 0
	v_cvt_pk_bf16_f32 v3, v4, v5
	ds_write_b64 v10, v[2:3]
	v_xad_u32 v10, v9, s79, v8
	ds_read_b64 v[2:3], v10
	v_pk_mul_f32 v[4:5], v[40:41], v[0:1] op_sel_hi:[1,0]
	s_waitcnt lgkmcnt(0)
	v_lshlrev_b32_e32 v6, 16, v2
	v_and_b32_e32 v7, 0xffff0000, v2
	v_pk_mul_f32 v[4:5], v[4:5], v[6:7]
	v_lshlrev_b32_e32 v6, 16, v3
	v_cvt_pk_bf16_f32 v2, v4, v5
	v_pk_mul_f32 v[4:5], v[42:43], v[0:1] op_sel_hi:[1,0]
	v_and_b32_e32 v7, 0xffff0000, v3
	v_pk_mul_f32 v[4:5], v[4:5], v[6:7]
	s_nop 0
	v_cvt_pk_bf16_f32 v3, v4, v5
	ds_write_b64 v10, v[2:3]
	v_xad_u32 v10, v9, s80, v8
	ds_read_b64 v[2:3], v10
	v_pk_mul_f32 v[4:5], v[44:45], v[0:1] op_sel_hi:[1,0]
	s_waitcnt lgkmcnt(0)
	v_lshlrev_b32_e32 v6, 16, v2
	v_and_b32_e32 v7, 0xffff0000, v2
	v_pk_mul_f32 v[4:5], v[4:5], v[6:7]
	v_lshlrev_b32_e32 v6, 16, v3
	v_cvt_pk_bf16_f32 v2, v4, v5
	v_pk_mul_f32 v[4:5], v[46:47], v[0:1] op_sel_hi:[1,0]
	v_and_b32_e32 v7, 0xffff0000, v3
	v_pk_mul_f32 v[4:5], v[4:5], v[6:7]
	s_nop 0
	v_cvt_pk_bf16_f32 v3, v4, v5
	ds_write_b64 v10, v[2:3]
	v_xad_u32 v10, v9, s81, v8
	ds_read_b64 v[2:3], v10
	v_pk_mul_f32 v[4:5], v[16:17], v[0:1] op_sel_hi:[1,0]
	s_waitcnt lgkmcnt(0)
	v_lshlrev_b32_e32 v6, 16, v2
	v_and_b32_e32 v7, 0xffff0000, v2
	v_pk_mul_f32 v[4:5], v[4:5], v[6:7]
	v_lshlrev_b32_e32 v6, 16, v3
	v_cvt_pk_bf16_f32 v2, v4, v5
	v_pk_mul_f32 v[4:5], v[18:19], v[0:1] op_sel_hi:[1,0]
	v_and_b32_e32 v7, 0xffff0000, v3
	v_pk_mul_f32 v[4:5], v[4:5], v[6:7]
	s_nop 0
	v_cvt_pk_bf16_f32 v3, v4, v5
	ds_write_b64 v10, v[2:3]
	v_xad_u32 v10, v9, s82, v8
	ds_read_b64 v[2:3], v10
	v_pk_mul_f32 v[4:5], v[20:21], v[0:1] op_sel_hi:[1,0]
	s_waitcnt lgkmcnt(0)
	v_lshlrev_b32_e32 v6, 16, v2
	v_and_b32_e32 v7, 0xffff0000, v2
	v_pk_mul_f32 v[4:5], v[4:5], v[6:7]
	v_lshlrev_b32_e32 v6, 16, v3
	v_cvt_pk_bf16_f32 v2, v4, v5
	v_pk_mul_f32 v[4:5], v[22:23], v[0:1] op_sel_hi:[1,0]
	v_and_b32_e32 v7, 0xffff0000, v3
	v_pk_mul_f32 v[4:5], v[4:5], v[6:7]
	s_nop 0
	v_cvt_pk_bf16_f32 v3, v4, v5
	ds_write_b64 v10, v[2:3]
	v_xad_u32 v10, v9, s83, v8
	ds_read_b64 v[2:3], v10
	v_pk_mul_f32 v[4:5], v[24:25], v[0:1] op_sel_hi:[1,0]
	v_xad_u32 v8, v9, s84, v8
	s_waitcnt lgkmcnt(0)
	v_lshlrev_b32_e32 v6, 16, v2
	v_and_b32_e32 v7, 0xffff0000, v2
	v_pk_mul_f32 v[4:5], v[4:5], v[6:7]
	v_lshlrev_b32_e32 v6, 16, v3
	v_cvt_pk_bf16_f32 v2, v4, v5
	v_pk_mul_f32 v[4:5], v[26:27], v[0:1] op_sel_hi:[1,0]
	v_and_b32_e32 v7, 0xffff0000, v3
	v_pk_mul_f32 v[4:5], v[4:5], v[6:7]
	s_nop 0
	v_cvt_pk_bf16_f32 v3, v4, v5
	ds_write_b64 v10, v[2:3]
	ds_read_b64 v[2:3], v8
	v_pk_mul_f32 v[4:5], v[28:29], v[0:1] op_sel_hi:[1,0]
	s_waitcnt lgkmcnt(0)
	v_lshlrev_b32_e32 v6, 16, v2
	v_and_b32_e32 v7, 0xffff0000, v2
	v_pk_mul_f32 v[4:5], v[4:5], v[6:7]
	v_lshlrev_b32_e32 v6, 16, v3
	v_cvt_pk_bf16_f32 v2, v4, v5
	v_pk_mul_f32 v[4:5], v[30:31], v[0:1] op_sel_hi:[1,0]
	v_and_b32_e32 v7, 0xffff0000, v3
	v_pk_mul_f32 v[4:5], v[4:5], v[6:7]
	v_lshlrev_b32_e32 v0, 4, v174
	v_cvt_pk_bf16_f32 v3, v4, v5
	v_and_b32_e32 v0, 0xf0, v0
	ds_write_b64 v8, v[2:3]
	v_add_u32_e32 v18, s61, v0
	s_waitcnt lgkmcnt(0)
	v_lshl_add_u32 v6, v170, 8, v18
	ds_read_b128 v[2:5], v6
	v_mul_u32_u24_e32 v0, 0x1400, v170
	v_lshl_add_u64 v[14:15], s[0:1], 0, v[0:1]
	v_lshl_add_u64 v[10:11], v[14:15], 0, v[144:145]
	v_lshl_add_u32 v0, v147, 8, v18
	v_mov_b32_e32 v147, v1
	s_waitcnt lgkmcnt(0)
	global_store_dwordx4 v[10:11], v[2:5], off
	v_lshl_add_u64 v[10:11], v[14:15], 0, v[146:147]
	ds_read_b128 v[6:9], v6 offset:4096
	ds_read_b128 v[2:5], v0
	v_add_co_u32_e32 v16, vcc, s86, v10
	v_lshl_add_u32 v0, v149, 8, v18
	s_nop 0
	v_addc_co_u32_e32 v17, vcc, 0, v11, vcc
	ds_read_b128 v[10:13], v0
	v_lshl_add_u64 v[14:15], v[14:15], 0, s[48:49]
	v_mov_b32_e32 v149, v1
	s_waitcnt lgkmcnt(0)
	global_store_dwordx4 v[16:17], v[2:5], off
	v_lshl_add_u32 v0, v153, 8, v18
	v_mov_b32_e32 v153, v1
	v_lshl_add_u64 v[2:3], v[14:15], 0, v[148:149]
	global_store_dwordx4 v[2:3], v[10:13], off
	ds_read_b128 v[2:5], v0
	v_lshl_add_u32 v0, v151, 8, v18
	v_lshl_add_u64 v[10:11], v[14:15], 0, v[152:153]
	v_add_co_u32_e32 v14, vcc, s86, v10
	v_mov_b32_e32 v151, v1
	s_nop 0
	v_addc_co_u32_e32 v15, vcc, 0, v11, vcc
	ds_read_b128 v[10:13], v0
	v_mad_u32_u24 v0, v170, s85, v196
	s_waitcnt lgkmcnt(0)
	global_store_dwordx4 v[14:15], v[2:5], off
	s_nop 1
	v_lshl_add_u64 v[2:3], s[0:1], 0, v[0:1]
	v_lshl_add_u64 v[2:3], v[2:3], 0, v[144:145]
	v_mad_u32_u24 v0, v170, s85, v197
	global_store_dwordx4 v[2:3], v[6:9], off
	v_lshl_add_u64 v[2:3], s[0:1], 0, v[0:1]
	v_lshl_add_u64 v[2:3], v[2:3], 0, v[150:151]
	v_lshl_add_u32 v0, v155, 8, v18
	global_store_dwordx4 v[2:3], v[10:13], off
	ds_read_b128 v[2:5], v0
	v_mad_u32_u24 v0, v170, s85, v198
	v_lshl_add_u64 v[6:7], s[0:1], 0, v[0:1]
	v_mov_b32_e32 v155, v1
	v_lshl_add_u32 v0, v157, 8, v18
	v_lshl_add_u64 v[10:11], v[6:7], 0, v[154:155]
	ds_read_b128 v[6:9], v0
	v_mad_u32_u24 v0, v170, s85, v199
	s_waitcnt lgkmcnt(0)
	global_store_dwordx4 v[10:11], v[2:5], off
	v_mov_b32_e32 v157, v1
	s_nop 0
	v_lshl_add_u64 v[2:3], s[0:1], 0, v[0:1]
	v_lshl_add_u64 v[2:3], v[2:3], 0, v[156:157]
	global_store_dwordx4 v[2:3], v[6:9], off
	s_waitcnt lgkmcnt(0)

.LBB0_453:
	v_mov_b32_e32 v177, v78
	ds_read_b128 v[78:81], v5
	ds_read_b128 v[82:85], v5 offset:16
	ds_read_b128 v[86:89], v5 offset:64
	ds_read_b128 v[90:93], v5 offset:80
	ds_read_b128 v[94:97], v5 offset:128
	ds_read_b128 v[98:101], v5 offset:144
	ds_read_b128 v[102:105], v5 offset:192
	ds_read_b128 v[106:109], v5 offset:208
	ds_read_b128 v[162:165], v5 offset:256
	ds_read_b128 v[166:169], v5 offset:272
	ds_read_b128 v[178:181], v5 offset:320
	ds_read_b128 v[182:185], v5 offset:336
	ds_read_b128 v[200:203], v5 offset:384
	ds_read_b128 v[204:207], v5 offset:400
	ds_read_b128 v[208:211], v5 offset:448
	ds_read_b128 v[212:215], v5 offset:464
	s_waitcnt lgkmcnt(13)
	v_mov_b32_e32 v111, v86
	v_mov_b32_e32 v86, v79
	v_mov_b32_e32 v110, v78
	v_pk_mul_f32 v[86:87], v[86:87], v[10:11]
	v_mov_b32_e32 v78, v80
	v_mov_b32_e32 v79, v88
	v_mov_b32_e32 v88, v81
	s_waitcnt lgkmcnt(12)
	v_mov_b32_e32 v81, v90
	v_mov_b32_e32 v90, v83
	v_mov_b32_e32 v83, v92
	v_mov_b32_e32 v92, v85
	s_waitcnt lgkmcnt(9)
	v_mov_b32_e32 v85, v102
	v_mov_b32_e32 v102, v95
	v_pk_fma_f32 v[86:87], v[110:111], v[8:9], v[86:87]
	v_mov_b32_e32 v80, v82
	v_mov_b32_e32 v82, v84
	v_mov_b32_e32 v84, v94
	v_pk_mul_f32 v[102:103], v[102:103], v[26:27]
	v_pk_fma_f32 v[78:79], v[78:79], v[12:13], v[86:87]
	v_mov_b32_e32 v94, v96
	v_mov_b32_e32 v95, v104
	v_mov_b32_e32 v104, v97
	s_waitcnt lgkmcnt(8)
	v_mov_b32_e32 v97, v106
	v_mov_b32_e32 v106, v99
	v_mov_b32_e32 v99, v108
	v_mov_b32_e32 v108, v101
	s_waitcnt lgkmcnt(5)
	v_mov_b32_e32 v101, v178
	v_mov_b32_e32 v178, v163
	v_pk_fma_f32 v[84:85], v[84:85], v[24:25], v[102:103]
	v_pk_fma_f32 v[78:79], v[88:89], v[14:15], v[78:79]
	v_mov_b32_e32 v96, v98
	v_mov_b32_e32 v98, v100
	v_mov_b32_e32 v100, v162
	v_pk_mul_f32 v[178:179], v[178:179], v[42:43]
	v_pk_fma_f32 v[84:85], v[94:95], v[28:29], v[84:85]
	v_pk_fma_f32 v[78:79], v[80:81], v[16:17], v[78:79]
	v_mov_b32_e32 v162, v164
	v_mov_b32_e32 v163, v180
	v_mov_b32_e32 v180, v165
	s_waitcnt lgkmcnt(4)
	v_mov_b32_e32 v165, v182
	v_mov_b32_e32 v182, v167
	v_mov_b32_e32 v167, v184
	v_mov_b32_e32 v184, v169
	s_waitcnt lgkmcnt(1)
	v_mov_b32_e32 v169, v208
	v_mov_b32_e32 v208, v201
	v_pk_fma_f32 v[100:101], v[100:101], v[40:41], v[178:179]
	v_pk_fma_f32 v[84:85], v[104:105], v[30:31], v[84:85]
	v_pk_fma_f32 v[78:79], v[90:91], v[18:19], v[78:79]
	v_mov_b32_e32 v164, v166
	v_mov_b32_e32 v166, v168
	v_mov_b32_e32 v168, v200
	v_mov_b32_e32 v200, v202
	v_mov_b32_e32 v201, v210
	v_mov_b32_e32 v210, v203
	v_mov_b32_e32 v202, v204
	s_waitcnt lgkmcnt(0)
	v_mov_b32_e32 v203, v212
	v_mov_b32_e32 v212, v205
	v_mov_b32_e32 v204, v206
	v_mov_b32_e32 v205, v214
	v_mov_b32_e32 v214, v207
	v_pk_mul_f32 v[206:207], v[208:209], v[58:59]
	v_pk_fma_f32 v[86:87], v[162:163], v[44:45], v[100:101]
	v_pk_fma_f32 v[80:81], v[96:97], v[32:33], v[84:85]
	v_pk_fma_f32 v[78:79], v[82:83], v[20:21], v[78:79]
	v_pk_fma_f32 v[102:103], v[168:169], v[56:57], v[206:207]
	v_pk_fma_f32 v[86:87], v[180:181], v[46:47], v[86:87]
	v_pk_fma_f32 v[80:81], v[106:107], v[34:35], v[80:81]
	v_pk_fma_f32 v[78:79], v[92:93], v[22:23], v[78:79]
	v_pk_fma_f32 v[94:95], v[200:201], v[60:61], v[102:103]
	v_pk_fma_f32 v[84:85], v[164:165], v[48:49], v[86:87]
	v_pk_fma_f32 v[80:81], v[98:99], v[36:37], v[80:81]
	v_add_f32_e32 v78, 0, v78
	v_pk_fma_f32 v[88:89], v[210:211], v[62:63], v[94:95]
	v_pk_fma_f32 v[84:85], v[182:183], v[50:51], v[84:85]
	v_pk_fma_f32 v[80:81], v[108:109], v[38:39], v[80:81]
	v_add_f32_e32 v78, v78, v79
	v_pk_fma_f32 v[86:87], v[202:203], v[64:65], v[88:89]
	v_pk_fma_f32 v[82:83], v[166:167], v[52:53], v[84:85]
	v_add_f32_e32 v78, v78, v80
	v_pk_fma_f32 v[86:87], v[212:213], v[66:67], v[86:87]
	v_pk_fma_f32 v[82:83], v[184:185], v[54:55], v[82:83]
	v_add_f32_e32 v78, v78, v81
	v_pk_fma_f32 v[84:85], v[204:205], v[68:69], v[86:87]
	v_add_f32_e32 v78, v78, v82
	v_pk_fma_f32 v[84:85], v[214:215], v[70:71], v[84:85]
	v_add_f32_e32 v78, v78, v83
	v_add_f32_e32 v78, v78, v84
	v_add_f32_e32 v78, v78, v85
	v_mov_b32_e32 v79, v78
	s_nop 1
	v_permlane32_swap_b32_e32 v78, v79
	v_add_f32_e32 v79, v78, v79
	v_cmp_gt_f32_e32 vcc, v79, v76
	v_mov_b32_e32 v186, s56
	v_cmp_gt_f32_e64 s[0:1], v79, v77
	v_cndmask_b32_e32 v76, v76, v79, vcc
	s_add_i32 s56, s56, 1
	v_cndmask_b32_e64 v76, v76, v77, s[0:1]
	v_cndmask_b32_e64 v77, v77, v79, s[0:1]
	v_cmp_gt_f32_e64 s[2:3], v79, v7
	v_cndmask_b32_e32 v74, v74, v186, vcc
	v_cndmask_b32_e64 v80, v75, v186, s[0:1]
	v_add_u32_e32 v5, 0x200, v5
	s_cmp_lg_u32 s93, s56
	v_cndmask_b32_e64 v74, v74, v75, s[0:1]
	v_cndmask_b32_e64 v77, v77, v7, s[2:3]
	v_cndmask_b32_e64 v78, v177, v186, s[2:3]
	v_cndmask_b32_e64 v7, v7, v79, s[2:3]
	v_cndmask_b32_e64 v75, v80, v177, s[2:3]
	s_cbranch_scc1 .LBB0_453
	v_lshlrev_b32_e64 v5, v78, 1
	v_lshlrev_b32_e64 v7, v75, 1
	v_lshlrev_b32_e64 v8, v74, 1
	v_lshl_add_u64 v[164:165], v[0:1], 1, s[52:53]
	v_lshlrev_b32_e32 v0, 1, v3
	v_or3_b32 v178, v8, v5, v7
	v_mov_b32_e32 v5, v1
	v_lshl_add_u64 v[168:169], s[52:53], 0, v[0:1]
	v_lshlrev_b32_e32 v180, 2, v72
	v_bfe_u32 v0, v2, 2, 2
	v_lshrrev_b32_e32 v3, 3, v2
	v_bfe_u32 v2, v2, 1, 1
	v_lshl_add_u64 v[162:163], s[54:55], 0, v[4:5]
	v_and_or_b32 v2, v3, 2, v2
	v_lshlrev_b32_e32 v3, 2, v0
	v_lshlrev_b32_e32 v5, 3, v174
	v_or_b32_e32 v0, v180, v0
	v_or_b32_e32 v4, v3, v72
	v_and_b32_e32 v181, 8, v5
	v_xor_b32_e32 v5, v72, v145
	v_lshlrev_b32_e32 v203, 8, v0
	v_bitop3_b32 v0, v3, v2, v72 bitop3:0x36
	v_lshlrev_b32_e32 v182, 4, v5
	v_bitop3_b32 v5, v72, v145, 2 bitop3:0x36
	v_lshlrev_b32_e32 v204, 4, v0
	v_bitop3_b32 v0, v4, v2, 2 bitop3:0x36
	v_lshlrev_b32_e32 v183, 4, v5
	v_bitop3_b32 v5, v72, v145, 4 bitop3:0x36
	v_lshlrev_b32_e32 v205, 4, v0
	v_or_b32_e32 v0, 4, v2
	v_lshlrev_b32_e32 v184, 4, v5
	v_bitop3_b32 v5, v72, v145, 6 bitop3:0x36
	v_bitop3_b32 v0, v4, v0, 2 bitop3:0x36
	v_lshlrev_b32_e32 v185, 4, v5
	v_bitop3_b32 v5, v72, v145, 8 bitop3:0x36
	v_lshlrev_b32_e32 v207, 4, v0
	v_or_b32_e32 v0, 8, v2
	v_lshlrev_b32_e32 v186, 4, v5
	v_bitop3_b32 v5, v72, v145, 10 bitop3:0x36
	v_bitop3_b32 v0, v4, v0, 2 bitop3:0x36
	v_lshlrev_b32_e32 v200, 4, v5
	v_bitop3_b32 v5, v72, v145, 12 bitop3:0x36
	v_bitop3_b32 v3, v2, v4, 4 bitop3:0x36
	v_lshlrev_b32_e32 v209, 4, v0
	v_or_b32_e32 v0, 12, v2
	v_mov_b32_e32 v7, v1
	v_lshlrev_b32_e32 v201, 4, v5
	v_bitop3_b32 v5, v72, v145, 14 bitop3:0x36
	v_lshlrev_b32_e32 v206, 4, v3
	v_bitop3_b32 v3, v2, v4, 8 bitop3:0x36
	v_bitop3_b32 v2, v2, v4, 12 bitop3:0x36
	v_bitop3_b32 v0, v4, v0, 2 bitop3:0x36
	v_mov_b32_e32 v14, v1
	v_mov_b32_e32 v15, v1
	s_lshl_b32 s56, s93, 2
	v_lshl_add_u64 v[166:167], s[54:55], 0, v[6:7]
	v_lshlrev_b32_e32 v177, 8, v73
	v_lshlrev_b32_e32 v202, 4, v5
	v_lshlrev_b32_e32 v208, 4, v3
	v_lshlrev_b32_e32 v210, 4, v2
	v_lshlrev_b32_e32 v211, 4, v0
	v_mov_b32_e32 v0, v1
	v_mov_b32_e32 v2, v1
	v_mov_b32_e32 v3, v1
	v_mov_b32_e32 v4, v1
	v_mov_b32_e32 v5, v1
	v_mov_b32_e32 v6, v1
	v_mov_b32_e32 v8, v1
	v_mov_b32_e32 v9, v1
	v_mov_b32_e32 v10, v1
	v_mov_b32_e32 v11, v1
	v_mov_b32_e32 v12, v1
	v_mov_b32_e32 v13, v1
	v_mov_b64_e32 v[30:31], v[14:15]
	v_mov_b64_e32 v[46:47], v[14:15]
	v_mov_b64_e32 v[62:63], v[14:15]
	v_mov_b64_e32 v[78:79], v[14:15]
	s_add_i32 s56, s56, 4
	s_or_b32 s54, s94, 31
	v_add_u32_e32 v179, 0, v177
	s_mov_b32 s55, 0
	v_mov_b32_e32 v212, 0
	v_mov_b32_e32 v213, 0xf149f2ca
	s_mov_b32 s57, 0
	v_mov_b64_e32 v[28:29], v[12:13]
	v_mov_b64_e32 v[26:27], v[10:11]
	v_mov_b64_e32 v[24:25], v[8:9]
	v_mov_b64_e32 v[22:23], v[6:7]
	v_mov_b64_e32 v[20:21], v[4:5]
	v_mov_b64_e32 v[18:19], v[2:3]
	v_mov_b64_e32 v[16:17], v[0:1]
	v_mov_b64_e32 v[44:45], v[12:13]
	v_mov_b64_e32 v[42:43], v[10:11]
	v_mov_b64_e32 v[40:41], v[8:9]
	v_mov_b64_e32 v[38:39], v[6:7]
	v_mov_b64_e32 v[36:37], v[4:5]
	v_mov_b64_e32 v[34:35], v[2:3]
	v_mov_b64_e32 v[32:33], v[0:1]
	v_mov_b64_e32 v[60:61], v[12:13]
	v_mov_b64_e32 v[58:59], v[10:11]
	v_mov_b64_e32 v[56:57], v[8:9]
	v_mov_b64_e32 v[54:55], v[6:7]
	v_mov_b64_e32 v[52:53], v[4:5]
	v_mov_b64_e32 v[50:51], v[2:3]
	v_mov_b64_e32 v[48:49], v[0:1]
	v_mov_b64_e32 v[76:77], v[12:13]
	v_mov_b64_e32 v[74:75], v[10:11]
	v_mov_b64_e32 v[72:73], v[8:9]
	v_mov_b64_e32 v[70:71], v[6:7]
	v_mov_b64_e32 v[68:69], v[4:5]
	v_mov_b64_e32 v[66:67], v[2:3]
	v_mov_b64_e32 v[64:65], v[0:1]
	s_mov_b32 s59, 0
	s_cmp_lt_u32 s91, 0x2000
	s_cbranch_scc1 .Lsprio3
	s_setprio 1

.LBB0_468:
	v_sub_f32_e32 v8, v82, v2
	v_sub_f32_e32 v9, v83, v2
	v_sub_f32_e32 v7, v98, v2
	v_exp_f32_e32 v98, v8
	v_sub_f32_e32 v8, v99, v2
	v_exp_f32_e32 v99, v9
	v_sub_f32_e32 v9, v100, v2
	v_exp_f32_e32 v12, v9
	v_sub_f32_e32 v9, v84, v2
	v_exp_f32_e32 v100, v9
	v_sub_f32_e32 v9, v101, v2
	v_exp_f32_e32 v13, v9
	v_sub_f32_e32 v9, v85, v2
	v_exp_f32_e32 v101, v9
	v_sub_f32_e32 v9, v102, v2
	v_exp_f32_e32 v14, v9
	v_sub_f32_e32 v9, v86, v2
	v_exp_f32_e32 v102, v9
	v_sub_f32_e32 v9, v103, v2
	v_exp_f32_e32 v15, v9
	v_sub_f32_e32 v9, v87, v2
	v_sub_f32_e32 v3, v96, v2
	v_sub_f32_e32 v4, v80, v2
	v_exp_f32_e32 v103, v9
	v_sub_f32_e32 v9, v104, v2
	v_exp_f32_e32 v3, v3
	v_exp_f32_e32 v96, v4
	v_sub_f32_e32 v4, v97, v2
	v_sub_f32_e32 v5, v81, v2
	v_exp_f32_e32 v104, v9
	v_sub_f32_e32 v9, v88, v2
	v_exp_f32_e32 v4, v4
	v_exp_f32_e32 v97, v5
	v_exp_f32_e32 v88, v9
	v_sub_f32_e32 v9, v105, v2
	v_exp_f32_e32 v7, v7
	v_exp_f32_e32 v105, v9
	v_sub_f32_e32 v9, v89, v2
	v_exp_f32_e32 v8, v8
	v_exp_f32_e32 v89, v9
	v_sub_f32_e32 v9, v106, v2
	v_add_f32_e32 v5, v3, v96
	v_exp_f32_e32 v106, v9
	v_sub_f32_e32 v9, v90, v2
	v_add_f32_e32 v5, 0, v5
	v_add_f32_e32 v6, v4, v97
	v_exp_f32_e32 v90, v9
	v_sub_f32_e32 v9, v107, v2
	v_add_f32_e32 v5, v6, v5
	v_add_f32_e32 v6, v7, v98
	v_exp_f32_e32 v107, v9
	v_sub_f32_e32 v9, v91, v2
	v_add_f32_e32 v5, v6, v5
	v_add_f32_e32 v6, v8, v99
	v_exp_f32_e32 v91, v9
	v_sub_f32_e32 v9, v108, v2
	v_add_f32_e32 v5, v6, v5
	v_add_f32_e32 v6, v12, v100
	v_exp_f32_e32 v108, v9
	v_sub_f32_e32 v9, v92, v2
	v_add_f32_e32 v5, v6, v5
	v_add_f32_e32 v6, v13, v101
	v_exp_f32_e32 v92, v9
	v_sub_f32_e32 v9, v109, v2
	v_add_f32_e32 v5, v6, v5
	v_add_f32_e32 v6, v14, v102
	v_exp_f32_e32 v109, v9
	v_sub_f32_e32 v9, v93, v2
	v_add_f32_e32 v5, v6, v5
	v_add_f32_e32 v6, v15, v103
	v_exp_f32_e32 v93, v9
	v_sub_f32_e32 v9, v110, v2
	v_add_f32_e32 v5, v6, v5
	v_add_f32_e32 v6, v104, v88
	v_exp_f32_e32 v110, v9
	v_sub_f32_e32 v9, v94, v2
	v_add_f32_e32 v5, v6, v5
	v_add_f32_e32 v6, v105, v89
	v_exp_f32_e32 v94, v9
	v_sub_f32_e32 v9, v111, v2
	v_add_f32_e32 v5, v6, v5
	v_add_f32_e32 v6, v106, v90
	v_exp_f32_e32 v111, v9
	v_sub_f32_e32 v9, v95, v2
	v_add_f32_e32 v5, v6, v5
	v_add_f32_e32 v6, v107, v91
	v_exp_f32_e32 v95, v9
	v_add_f32_e32 v5, v6, v5
	v_add_f32_e32 v6, v108, v92
	v_add_f32_e32 v5, v6, v5
	v_add_f32_e32 v6, v109, v93
	v_add_f32_e32 v5, v6, v5
	v_add_f32_e32 v6, v110, v94
	v_add_f32_e32 v5, v6, v5
	v_add_f32_e32 v6, v111, v95
	v_add_f32_e32 v213, v6, v5
	v_fmac_f32_e32 v213, v212, v0
	s_add_i32 s0, s2, 0
	s_nop 0
	v_add_u32_e32 v0, s0, v181
	v_add_u32_e32 v212, s0, v203
	v_cvt_pk_bf16_f32 v4, v3, v4
	v_add3_u32 v3, v0, v204, v203
	v_add3_u32 v86, v212, v205, v181
	v_cvt_pk_bf16_f32 v5, v7, v8
	s_nop 0
	ds_read_b64_tr_b16 v[8:9], v3 offset:32768
	ds_read_b64_tr_b16 v[10:11], v86 offset:34816
	v_cvt_pk_bf16_f32 v6, v12, v13
	v_cvt_pk_bf16_f32 v7, v14, v15
	ds_read_b64_tr_b16 v[12:13], v3 offset:36864
	ds_read_b64_tr_b16 v[80:81], v3 offset:40960
	ds_read_b64_tr_b16 v[84:85], v3 offset:45056
	ds_read_b64_tr_b16 v[14:15], v86 offset:38912
	ds_read_b64_tr_b16 v[82:83], v86 offset:43008
	ds_read_b64_tr_b16 v[86:87], v86 offset:47104
	s_waitcnt lgkmcnt(6)
	v_mfma_f32_32x32x16_bf16 v[64:79], v[8:11], v[4:7], v[64:79]
	v_cvt_pk_bf16_f32 v8, v104, v105
	v_cvt_pk_bf16_f32 v9, v106, v107
	v_cvt_pk_bf16_f32 v10, v108, v109
	v_cvt_pk_bf16_f32 v11, v110, v111
	v_add3_u32 v3, v0, v206, v203
	s_waitcnt lgkmcnt(2)
	v_mfma_f32_32x32x16_bf16 v[64:79], v[12:15], v[8:11], v[64:79]
	v_cvt_pk_bf16_f32 v12, v96, v97
	v_cvt_pk_bf16_f32 v13, v98, v99
	v_cvt_pk_bf16_f32 v14, v100, v101
	v_cvt_pk_bf16_f32 v15, v102, v103
	v_add3_u32 v100, v212, v207, v181
	s_waitcnt lgkmcnt(1)
	v_mfma_f32_32x32x16_bf16 v[64:79], v[80:83], v[12:15], v[64:79]
	v_cvt_pk_bf16_f32 v80, v88, v89
	ds_read_b64_tr_b16 v[88:89], v100 offset:34816
	v_cvt_pk_bf16_f32 v81, v90, v91
	v_cvt_pk_bf16_f32 v82, v92, v93
	v_cvt_pk_bf16_f32 v83, v94, v95
	s_waitcnt lgkmcnt(1)
	s_nop 0
	v_mfma_f32_32x32x16_bf16 v[64:79], v[84:87], v[80:83], v[64:79]
	ds_read_b64_tr_b16 v[86:87], v3 offset:32768
	ds_read_b64_tr_b16 v[90:91], v3 offset:36864
	ds_read_b64_tr_b16 v[94:95], v3 offset:40960
	ds_read_b64_tr_b16 v[98:99], v3 offset:45056
	ds_read_b64_tr_b16 v[92:93], v100 offset:38912
	ds_read_b64_tr_b16 v[96:97], v100 offset:43008
	ds_read_b64_tr_b16 v[100:101], v100 offset:47104
	v_add3_u32 v3, v0, v208, v203
	v_add3_u32 v0, v0, v210, v203
	s_waitcnt lgkmcnt(6)
	v_mfma_f32_32x32x16_bf16 v[48:63], v[86:89], v[4:7], v[48:63]
	s_waitcnt lgkmcnt(2)
	v_mfma_f32_32x32x16_bf16 v[48:63], v[90:93], v[8:11], v[48:63]
	s_waitcnt lgkmcnt(1)
	v_mfma_f32_32x32x16_bf16 v[48:63], v[94:97], v[12:15], v[48:63]
	s_waitcnt lgkmcnt(0)
	v_mfma_f32_32x32x16_bf16 v[48:63], v[98:101], v[80:83], v[48:63]
	v_add3_u32 v98, v212, v209, v181
	ds_read_b64_tr_b16 v[86:87], v98 offset:34816
	ds_read_b64_tr_b16 v[84:85], v3 offset:32768
	ds_read_b64_tr_b16 v[88:89], v3 offset:36864
	ds_read_b64_tr_b16 v[92:93], v3 offset:40960
	ds_read_b64_tr_b16 v[96:97], v3 offset:45056
	ds_read_b64_tr_b16 v[90:91], v98 offset:38912
	ds_read_b64_tr_b16 v[94:95], v98 offset:43008
	ds_read_b64_tr_b16 v[98:99], v98 offset:47104
	v_add3_u32 v3, v212, v211, v181
	v_mov_b32_e32 v212, v213
	s_waitcnt lgkmcnt(6)
	v_mfma_f32_32x32x16_bf16 v[32:47], v[84:87], v[4:7], v[32:47]
	s_waitcnt lgkmcnt(2)
	v_mfma_f32_32x32x16_bf16 v[32:47], v[88:91], v[8:11], v[32:47]
	s_waitcnt lgkmcnt(1)
	v_mfma_f32_32x32x16_bf16 v[32:47], v[92:95], v[12:15], v[32:47]
	s_waitcnt lgkmcnt(0)
	v_mfma_f32_32x32x16_bf16 v[32:47], v[96:99], v[80:83], v[32:47]
	ds_read_b64_tr_b16 v[86:87], v3 offset:34816
	ds_read_b64_tr_b16 v[84:85], v0 offset:32768
	ds_read_b64_tr_b16 v[88:89], v0 offset:36864
	ds_read_b64_tr_b16 v[92:93], v0 offset:40960
	ds_read_b64_tr_b16 v[96:97], v0 offset:45056
	ds_read_b64_tr_b16 v[90:91], v3 offset:38912
	ds_read_b64_tr_b16 v[94:95], v3 offset:43008
	ds_read_b64_tr_b16 v[98:99], v3 offset:47104
	s_waitcnt lgkmcnt(6)
	v_mfma_f32_32x32x16_bf16 v[16:31], v[84:87], v[4:7], v[16:31]
	s_waitcnt lgkmcnt(2)
	v_mfma_f32_32x32x16_bf16 v[16:31], v[88:91], v[8:11], v[16:31]
	s_waitcnt lgkmcnt(1)
	v_mfma_f32_32x32x16_bf16 v[16:31], v[92:95], v[12:15], v[16:31]
	s_waitcnt lgkmcnt(0)
	v_mfma_f32_32x32x16_bf16 v[16:31], v[96:99], v[80:83], v[16:31]
	s_add_i32 s57, s57, 64
	s_addk_i32 s55, 0x4000
	s_cmp_lg_u32 s56, s58
	s_cbranch_scc1 .LBB0_456
	s_branch .LBB0_262

.LBB0_596:
	s_lshl_b32 s98, s56, 3
	s_add_i32 s98, s98, s2
	s_mul_i32 s98, s98, 3
	v_lshl_add_u32 v164, s56, 8, v172
	s_cmp_eq_u32 s87, 3
	v_mad_i64_i32 v[162:163], s[56:57], v164, s77, v[156:157]
	s_cselect_b64 s[62:63], -1, 0
	s_lshl_b32 s56, s2, 8
	s_ashr_i32 s57, s56, 31
	v_lshl_add_u64 v[2:3], s[56:57], 1, v[162:163]
	s_mov_b32 s7, s3
	v_lshl_add_u64 v[2:3], v[2:3], 0, s[6:7]
	v_lshl_add_u64 v[166:167], v[2:3], 0, v[160:161]
	s_add_i32 s7, s88, -2
	s_add_u32 s89, s60, 0x100
	v_mov_b32_e32 v1, v0
	v_ashrrev_i32_e32 v165, 31, v164
	s_addc_u32 s90, s61, 0
	v_lshl_add_u64 v[168:169], s[58:59], 0, v[152:153]
	v_lshl_add_u64 v[170:171], s[58:59], 0, v[154:155]
	s_mov_b32 s64, 0
	s_mov_b64 s[60:61], 0
	s_xor_b64 s[62:63], s[62:63], -1
	v_add_u32_e32 v1, s79, v173
	s_add_i32 s2, s64, 2
	ds_read_b128 v[132:135], v1
	ds_read_b128 v[136:139], v1 offset:1024
	ds_read_b128 v[140:143], v1 offset:2048
	ds_read_b128 v[178:181], v1 offset:3072
	v_add_u32_e32 v1, s80, v173
	s_add_u32 s65, s58, s60
	ds_read_b128 v[182:185], v1
	ds_read_b128 v[188:191], v1 offset:1024
	ds_read_b128 v[192:195], v1 offset:2048
	ds_read_b128 v[196:199], v1 offset:3072
	s_addc_u32 s66, s59, s61
	s_add_u32 s65, s65, 0x100
	s_addc_u32 s66, s66, 0
	s_add_u32 s75, s89, s60
	s_addc_u32 s91, s90, s61
	s_cmp_eq_u32 s7, s64
	s_cselect_b32 s67, s51, s66
	s_cselect_b32 s66, s50, s65
	s_cselect_b32 s65, s53, s91
	s_cselect_b32 s64, s52, s75
	v_lshl_add_u64 v[2:3], v[168:169], 0, s[60:61]
	s_add_i32 m0, s69, 0xc000
	ds_read_b128 v[200:203], v174
	ds_read_b128 v[204:207], v174 offset:1024
	ds_read_b128 v[208:211], v174 offset:2048
	ds_read_b128 v[212:215], v174 offset:3072
	ds_read_b128 v[216:219], v174 offset:4096
	ds_read_b128 v[220:223], v174 offset:5120
	ds_read_b128 v[224:227], v174 offset:6144
	ds_read_b128 v[228:231], v174 offset:7168
	global_load_lds_dwordx4 v[2:3], off
	v_lshl_add_u64 v[2:3], v[170:171], 0, s[60:61]
	s_add_i32 m0, s69, 0xe000
	s_nop 0
	global_load_lds_dwordx4 v[2:3], off
	s_waitcnt vmcnt(8) lgkmcnt(0)
	s_setprio 1
	s_barrier
	v_mfma_f32_16x16x32_bf16 v[128:131], v[132:135], v[200:203], 0
	v_mfma_f32_16x16x32_bf16 v[124:127], v[140:143], v[200:203], 0
	v_mfma_f32_16x16x32_bf16 v[112:115], v[132:135], v[208:211], 0
	v_mfma_f32_16x16x32_bf16 v[108:111], v[140:143], v[208:211], 0
	v_mfma_f32_16x16x32_bf16 v[96:99], v[132:135], v[216:219], 0
	v_mfma_f32_16x16x32_bf16 v[92:95], v[140:143], v[216:219], 0
	v_mfma_f32_16x16x32_bf16 v[80:83], v[132:135], v[224:227], 0
	v_mfma_f32_16x16x32_bf16 v[76:79], v[140:143], v[224:227], 0
	v_mfma_f32_16x16x32_bf16 v[128:131], v[136:139], v[204:207], v[128:131]
	v_mfma_f32_16x16x32_bf16 v[124:127], v[178:181], v[204:207], v[124:127]
	v_mfma_f32_16x16x32_bf16 v[112:115], v[136:139], v[212:215], v[112:115]
	v_mfma_f32_16x16x32_bf16 v[108:111], v[178:181], v[212:215], v[108:111]
	v_mfma_f32_16x16x32_bf16 v[96:99], v[136:139], v[220:223], v[96:99]
	v_mfma_f32_16x16x32_bf16 v[92:95], v[178:181], v[220:223], v[92:95]
	v_mfma_f32_16x16x32_bf16 v[80:83], v[136:139], v[228:231], v[80:83]
	v_mfma_f32_16x16x32_bf16 v[76:79], v[178:181], v[228:231], v[76:79]
	s_setprio 0
	s_setprio 1
	v_mfma_f32_16x16x32_bf16 v[120:123], v[182:185], v[200:203], 0
	v_mfma_f32_16x16x32_bf16 v[116:119], v[192:195], v[200:203], 0
	v_mfma_f32_16x16x32_bf16 v[104:107], v[182:185], v[208:211], 0
	v_mfma_f32_16x16x32_bf16 v[100:103], v[192:195], v[208:211], 0
	v_mfma_f32_16x16x32_bf16 v[88:91], v[182:185], v[216:219], 0
	v_mfma_f32_16x16x32_bf16 v[84:87], v[192:195], v[216:219], 0
	v_mfma_f32_16x16x32_bf16 v[72:75], v[182:185], v[224:227], 0
	v_mfma_f32_16x16x32_bf16 v[68:71], v[192:195], v[224:227], 0
	v_mfma_f32_16x16x32_bf16 v[120:123], v[188:191], v[204:207], v[120:123]
	v_mfma_f32_16x16x32_bf16 v[116:119], v[196:199], v[204:207], v[116:119]
	v_mfma_f32_16x16x32_bf16 v[104:107], v[188:191], v[212:215], v[104:107]
	v_mfma_f32_16x16x32_bf16 v[100:103], v[196:199], v[212:215], v[100:103]
	v_mfma_f32_16x16x32_bf16 v[88:91], v[188:191], v[220:223], v[88:91]
	v_mfma_f32_16x16x32_bf16 v[84:87], v[196:199], v[220:223], v[84:87]
	v_mfma_f32_16x16x32_bf16 v[72:75], v[188:191], v[228:231], v[72:75]
	v_mfma_f32_16x16x32_bf16 v[68:71], v[196:199], v[228:231], v[68:71]
	s_barrier
	s_setprio 0
	s_add_i32 s75, s79, s68
	v_lshl_add_u64 v[232:233], s[64:65], 0, v[148:149]
	s_mov_b32 m0, s75
	ds_read_b128 v[200:203], v174 offset:16384
	ds_read_b128 v[204:207], v174 offset:17408
	ds_read_b128 v[208:211], v174 offset:18432
	ds_read_b128 v[212:215], v174 offset:19456
	ds_read_b128 v[216:219], v174 offset:20480
	ds_read_b128 v[220:223], v174 offset:21504
	ds_read_b128 v[224:227], v174 offset:22528
	ds_read_b128 v[228:231], v174 offset:23552
	global_load_lds_dwordx4 v[232:233], off
	s_add_i32 m0, s75, 0x2000
	s_add_u32 s92, s64, 0xa0000
	v_lshl_add_u64 v[234:235], s[64:65], 0, v[144:145]
	s_addc_u32 s93, s65, 0
	s_add_i32 s75, s80, s68
	global_load_lds_dwordx4 v[234:235], off
	v_lshl_add_u64 v[2:3], s[92:93], 0, v[148:149]
	s_mov_b32 m0, s75
	v_lshl_add_u64 v[236:237], s[66:67], 0, v[150:151]
	global_load_lds_dwordx4 v[2:3], off
	v_lshl_add_u64 v[2:3], s[92:93], 0, v[144:145]
	s_add_i32 m0, s75, 0x2000
	v_lshl_add_u64 v[238:239], s[66:67], 0, v[146:147]
	global_load_lds_dwordx4 v[2:3], off
	s_mov_b32 m0, s69
	s_nop 0
	global_load_lds_dwordx4 v[236:237], off
	s_mov_b32 m0, s70
	s_nop 0
	global_load_lds_dwordx4 v[238:239], off
	s_waitcnt vmcnt(8) lgkmcnt(0)
	s_setprio 1
	s_barrier
	v_mfma_f32_16x16x32_bf16 v[64:67], v[132:135], v[200:203], 0
	v_mfma_f32_16x16x32_bf16 v[60:63], v[140:143], v[200:203], 0
	v_mfma_f32_16x16x32_bf16 v[48:51], v[132:135], v[208:211], 0
	v_mfma_f32_16x16x32_bf16 v[44:47], v[140:143], v[208:211], 0
	v_mfma_f32_16x16x32_bf16 v[32:35], v[132:135], v[216:219], 0
	v_mfma_f32_16x16x32_bf16 v[28:31], v[140:143], v[216:219], 0
	v_mfma_f32_16x16x32_bf16 v[16:19], v[132:135], v[224:227], 0
	v_mfma_f32_16x16x32_bf16 v[12:15], v[140:143], v[224:227], 0
	v_mfma_f32_16x16x32_bf16 v[64:67], v[136:139], v[204:207], v[64:67]
	v_mfma_f32_16x16x32_bf16 v[60:63], v[178:181], v[204:207], v[60:63]
	v_mfma_f32_16x16x32_bf16 v[48:51], v[136:139], v[212:215], v[48:51]
	v_mfma_f32_16x16x32_bf16 v[44:47], v[178:181], v[212:215], v[44:47]
	v_mfma_f32_16x16x32_bf16 v[32:35], v[136:139], v[220:223], v[32:35]
	v_mfma_f32_16x16x32_bf16 v[28:31], v[178:181], v[220:223], v[28:31]
	v_mfma_f32_16x16x32_bf16 v[16:19], v[136:139], v[228:231], v[16:19]
	v_mfma_f32_16x16x32_bf16 v[12:15], v[178:181], v[228:231], v[12:15]
	s_setprio 0
	s_setprio 1
	v_mfma_f32_16x16x32_bf16 v[56:59], v[182:185], v[200:203], 0
	v_mfma_f32_16x16x32_bf16 v[52:55], v[192:195], v[200:203], 0
	v_mfma_f32_16x16x32_bf16 v[40:43], v[182:185], v[208:211], 0
	v_mfma_f32_16x16x32_bf16 v[36:39], v[192:195], v[208:211], 0
	v_mfma_f32_16x16x32_bf16 v[24:27], v[182:185], v[216:219], 0
	v_mfma_f32_16x16x32_bf16 v[20:23], v[192:195], v[216:219], 0
	v_mfma_f32_16x16x32_bf16 v[8:11], v[182:185], v[224:227], 0
	v_mfma_f32_16x16x32_bf16 v[2:5], v[192:195], v[224:227], 0
	v_mfma_f32_16x16x32_bf16 v[56:59], v[188:191], v[204:207], v[56:59]
	v_mfma_f32_16x16x32_bf16 v[52:55], v[196:199], v[204:207], v[52:55]
	v_mfma_f32_16x16x32_bf16 v[40:43], v[188:191], v[212:215], v[40:43]
	v_mfma_f32_16x16x32_bf16 v[36:39], v[196:199], v[212:215], v[36:39]
	v_mfma_f32_16x16x32_bf16 v[24:27], v[188:191], v[220:223], v[24:27]
	v_mfma_f32_16x16x32_bf16 v[20:23], v[196:199], v[220:223], v[20:23]
	v_mfma_f32_16x16x32_bf16 v[8:11], v[188:191], v[228:231], v[8:11]
	v_mfma_f32_16x16x32_bf16 v[2:5], v[196:199], v[228:231], v[2:5]
	s_barrier
	s_setprio 0
	s_branch .Lpeel_mid_p3
	s_nop 0
